# per-batch work remapped to the 32 workgroups with blockIdx%8==batch; 9 of 10 grid barriers replaced by 32-workgroup batch barriers
# speedup vs baseline: 1.0165x; 1.0165x over previous
; #define LAS __attribute__((address_space(3)))
; __device__ __forceinline__ unsigned xb_add(unsigned* p, unsigned v) { return __hip_atomic_fetch_add(p, v, __ATOMIC_RELAXED, __HIP_MEMORY_SCOPE_AGENT); }
; __device__ __forceinline__ unsigned xb_xcc_id() { return (unsigned)__builtin_amdgcn_s_getreg((3 << 11) | 20) & 0xFu; }
; __device__ __forceinline__ XcdBarrier xcd_barrier_post(unsigned* bar, volatile LAS unsigned* st) {
;     XcdBarrier b; b.bar = bar; b.x = xb_xcc_id(); b.st = st;
;     if (threadIdx.x == 0) (void)xb_add(&bar[XB_XCNT(b.x)], 1u);
;     return b;
; }
; __global__ void __launch_bounds__(512) hymba_fwd(Args a) {
;     ...
;     volatile LAS unsigned* xst = (volatile LAS unsigned*)(lds + LDS_BYTES - 16);
;     if (threadIdx.x < 2) xst[threadIdx.x] = 0u;
;     __syncthreads();
;     XcdBarrier xbar; xbar.bar = (unsigned*)(a.ws + WS_BAR); xbar.x = 0; xbar.st = xst;
;     if (hi - lo > 1) xbar = xcd_barrier_post((unsigned*)(a.ws + WS_BAR), xst);
_Z9hymba_fwd4Args:
	s_mov_b32 s100, 0
	s_mov_b32 s101, 0
	s_load_dwordx16 s[64:79], s[0:1], 0x40
	s_load_dwordx2 s[4:5], s[0:1], 0x80
	s_load_dword s3, s[0:1], 0x90
	v_and_b32_e32 v178, 0x3ff, v0
	v_cmp_gt_u32_e32 vcc, 2, v178
	s_waitcnt lgkmcnt(0)
	v_writelane_b32 v246, s4, 0
	s_nop 1
	v_writelane_b32 v246, s5, 1
	s_add_u32 s4, s0, 0x90
	s_addc_u32 s5, s1, 0
	v_writelane_b32 v246, s4, 2
	s_nop 1
	v_writelane_b32 v246, s5, 3
	s_and_saveexec_b64 s[4:5], vcc
	v_lshl_add_u32 v1, v178, 2, 0
	v_add_u32_e32 v1, 0x23ff0, v1
	v_mov_b32_e32 v2, 0
	ds_write_b32 v1, v2
	s_or_b64 exec, exec, s[4:5]
	s_load_dwordx2 s[4:5], s[0:1], 0x80
	s_load_dwordx16 s[80:95], s[0:1], 0x0
	s_add_u32 s12, s78, 0xfc00000
	s_addc_u32 s13, s79, 0
	s_mov_b32 s48, 0
	s_waitcnt lgkmcnt(0)
	s_sub_i32 s4, s5, s4
	s_cmp_lt_i32 s4, 2
	v_cmp_eq_u32_e32 vcc, 0, v178
	s_barrier
	s_cbranch_scc1 .LBB0_7
	s_getreg_b32 s4, hwreg(HW_REG_XCC_ID, 0, 4)
	s_and_b32 s48, s4, 15
	s_and_saveexec_b64 s[4:5], vcc
	s_cbranch_execz .LBB0_6
	s_mov_b64 s[6:7], exec
	v_mbcnt_lo_u32_b32 v1, s6, 0
	v_mbcnt_hi_u32_b32 v1, s7, v1
	v_cmp_eq_u32_e32 vcc, 0, v1
	s_and_b64 s[8:9], exec, vcc
	s_mov_b64 exec, s[8:9]
	s_cbranch_execz .LBB0_6
	s_lshl_b32 s8, s48, 8
	s_bcnt1_i32_b64 s6, s[6:7]
	v_mov_b32_e32 v1, s8
	v_mov_b32_e32 v2, s6
	global_atomic_add v1, v2, s[12:13] offset:1024
	s_and_b32 s98, s2, 7
	s_lshl_b32 s98, s98, 6
	s_lshl_b32 s99, 1, s48
	v_mov_b32_e32 v3, s98
	v_mov_b32_e32 v4, s99
	global_atomic_or v3, v4, s[12:13] offset:32

; #define LAS __attribute__((address_space(3)))
; __device__ __forceinline__ int otid() { int t = threadIdx.x; asm volatile("" : "+v"(t)); return t; }
; __global__ void __launch_bounds__(512) hymba_fwd(Args a) {
;     extern __shared__ __attribute__((aligned(16))) unsigned char lds_raw[];
;     LAS unsigned char* lds = (LAS unsigned char*)lds_raw;
;     const int G = gridDim.x, bx = blockIdx.x;
;     const int lo = a.ph_lo, hi = a.ph_hi;
;     bf16_t* proj = (bf16_t*)(a.ws + WS_PROJ);
;     ...
;     volatile LAS unsigned* xst = (volatile LAS unsigned*)(lds + LDS_BYTES - 16);
;     if (threadIdx.x < 2) xst[threadIdx.x] = 0u;
;     __syncthreads();
;     XcdBarrier xbar; xbar.bar = (unsigned*)(a.ws + WS_BAR); xbar.x = 0; xbar.st = xst;
;     if (hi - lo > 1) xbar = xcd_barrier_post((unsigned*)(a.ws + WS_BAR), xst);
;     ...
;             if (bx >= NKV) {
;                 const int wb = bx - NKV, WG = G - NKV;
;                 const int tid = otid();
;                 if (tid < 128) ((LAS float*)(lds + 68608))[tid] = (tid < 64) ? a.mqn[l * 64 + tid] : a.mkn[l * 64 + tid - 64];
;                 if (tid < 512) ((LAS float*)(lds + 106496))[tid] = ((const float*)(a.ws + WS_LB))[l * 512 + tid];
;                 __syncthreads();
;                 { PrepIn cur; int u = wb; moba_prep_load(a, tid, u < 512 ? u : 0, cur);
;                   for (; u < 512; u += WG) { PrepIn nxt; moba_prep_unit(a, l, lds, tid, u, cur, nxt, (u + WG < 512) ? u + WG : u); cur = nxt; } }
.LBB0_152:
	s_add_u32 s84, s78, 0x4600000
	s_addc_u32 s85, s79, 0
	s_add_u32 s88, s78, 0x1e00000
	s_addc_u32 s89, s79, 0
	s_add_u32 s33, s78, 0xc600000
	s_addc_u32 s20, s79, 0
	s_add_u32 s21, s78, 0xd600000
	s_addc_u32 s22, s79, 0
	s_cmpk_eq_i32 s3, 0x100
	s_cselect_b64 s[54:55], -1, 0
	s_cmpk_lg_i32 s3, 0x100
	s_movk_i32 s0, 0x100
	s_cselect_b64 s[56:57], -1, 0
	s_ashr_i32 s23, s3, 31
	s_ashr_i32 s24, s2, 31
	v_cmp_gt_u32_e64 s[8:9], s0, v178
	s_add_u32 s0, s78, 0xfa00000
	s_addc_u32 s1, s79, 0
	s_waitcnt vmcnt(3)
	v_mov_b32_e32 v145, 0
	v_lshlrev_b32_e32 v144, 2, v178
	v_writelane_b32 v246, s0, 4
	v_lshrrev_b32_e32 v1, 20, v0
	v_lshrrev_b32_e32 v0, 10, v0
	v_writelane_b32 v246, s1, 5
	v_lshl_add_u64 v[146:147], s[0:1], 0, v[144:145]
	s_add_i32 s0, 0, 0x20000
	s_cmpk_lt_i32 s2, 0x500
	v_add_u32_e32 v184, s0, v144
	s_cselect_b64 s[10:11], -1, 0
	s_lshr_b32 s0, s24, 29
	v_writelane_b32 v246, s8, 6
	s_add_i32 s0, s2, s0
	s_ashr_i32 s4, s0, 3
	v_writelane_b32 v246, s9, 7
	s_and_b32 s0, s0, -8
	v_writelane_b32 v246, s10, 8
	s_sub_i32 s0, s2, s0
	s_and_b64 s[8:9], s[10:11], s[8:9]
	v_writelane_b32 v246, s11, 9
	v_writelane_b32 v246, s8, 10
	s_waitcnt lgkmcnt(0)
	s_cmpk_eq_i32 s49, 0x5eed
	v_or_b32_e32 v0, v0, v1
	v_writelane_b32 v246, s9, 11
	s_cselect_b64 s[8:9], -1, 0
	v_writelane_b32 v246, s8, 12
	s_movk_i32 s25, 0xa1
	s_mov_b32 s7, 0
	v_writelane_b32 v246, s9, 13
	s_add_u32 s8, s78, 0xfc00200
	s_addc_u32 s9, s79, 0
	v_writelane_b32 v246, s8, 14
	s_mov_b32 s15, s7
	v_mov_b32_e32 v179, v145
	v_writelane_b32 v246, s9, 15
	s_add_u32 s8, s78, 0xfc00400
	s_addc_u32 s9, s79, 0
	v_writelane_b32 v246, s8, 16
	v_and_b32_e32 v185, 63, v178
	s_mov_b64 s[44:45], 0x3e00000
	v_writelane_b32 v246, s9, 17
	s_add_u32 s8, s78, 0xfc00500
	s_addc_u32 s9, s79, 0
	v_writelane_b32 v246, s8, 18
	v_mov_b32_e32 v186, 0x358637bd
	s_mov_b64 s[64:65], 0x100
	v_writelane_b32 v246, s9, 19
	s_add_u32 s8, s78, 0xfc00600
	s_addc_u32 s9, s79, 0
	v_writelane_b32 v246, s8, 20
	v_mov_b32_e32 v187, 1
	s_mov_b32 s28, 0x800000
	v_writelane_b32 v246, s9, 21
	s_add_u32 s8, s78, 0xfc00700
	s_addc_u32 s9, s79, 0
	v_writelane_b32 v246, s8, 22
	s_mov_b32 s29, 0x3f317217
	s_mov_b32 s30, 0x7f800000
	v_writelane_b32 v246, s9, 23
	s_add_u32 s8, s78, 0xfc00800
	s_addc_u32 s9, s79, 0
	v_writelane_b32 v246, s8, 24
	s_mov_b32 s68, 0x3f803f80
	s_movk_i32 s31, 0x110
	v_writelane_b32 v246, s9, 25
	s_add_u32 s8, s78, 0xfc00900
	s_addc_u32 s9, s79, 0
	v_writelane_b32 v246, s8, 26
	s_mov_b32 s34, 0x4220000
	v_mov_b64_e32 v[148:149], 0x500
	v_writelane_b32 v246, s9, 27
	s_add_u32 s8, s78, 0xfc00a00
	s_addc_u32 s9, s79, 0
	v_writelane_b32 v246, s8, 28
	v_mov_b64_e32 v[150:151], 0x4ff
	v_mov_b32_e32 v190, 0x41b17218
	v_writelane_b32 v246, s9, 29
	s_add_u32 s8, s78, 0xfc00b00
	s_addc_u32 s9, s79, 0
	v_writelane_b32 v246, s8, 30
	v_mov_b32_e32 v191, 0xf149f2ca
	v_mov_b64_e32 v[152:153], 0x100
	v_writelane_b32 v246, s9, 31
	s_add_u32 s8, s78, 0xfc00c00
	s_addc_u32 s9, s79, 0
	v_writelane_b32 v246, s8, 32
	v_mov_b64_e32 v[154:155], 0xff
	s_nop 0
	v_writelane_b32 v246, s9, 33
	s_add_u32 s8, s78, 0xfc00d00
	s_addc_u32 s9, s79, 0
	v_writelane_b32 v246, s8, 34
	s_nop 1
	v_writelane_b32 v246, s9, 35
	s_add_u32 s8, s78, 0xfc00e00
	s_addc_u32 s9, s79, 0
	v_writelane_b32 v246, s8, 36
	s_nop 1
	v_writelane_b32 v246, s9, 37
	s_add_u32 s8, s78, 0xfc00f00
	s_addc_u32 s9, s79, 0
	v_writelane_b32 v246, s8, 38
	s_nop 1
	v_writelane_b32 v246, s9, 39
	s_add_u32 s8, s78, 0xfc01000
	s_addc_u32 s9, s79, 0
	v_writelane_b32 v246, s8, 40
	s_nop 1
	v_writelane_b32 v246, s9, 41
	s_add_u32 s8, s78, 0xfc01100
	s_addc_u32 s9, s79, 0
	v_writelane_b32 v246, s8, 42
	s_nop 1
	v_writelane_b32 v246, s9, 43
	s_add_u32 s8, s78, 0xfc01200
	s_addc_u32 s9, s79, 0
	v_writelane_b32 v246, s8, 44
	s_nop 1
	v_writelane_b32 v246, s9, 45
	s_add_u32 s8, s78, 0xfc01300
	s_addc_u32 s9, s79, 0
	v_writelane_b32 v246, s8, 46
	s_cmp_eq_u32 s48, 15
	s_nop 0
	v_writelane_b32 v246, s9, 47
	s_cselect_b64 s[8:9], -1, 0
	v_writelane_b32 v246, s8, 48
	s_cmp_eq_u32 s48, 14
	s_nop 0
	v_writelane_b32 v246, s9, 49
	s_cselect_b64 s[8:9], -1, 0
	v_writelane_b32 v246, s8, 50
	s_cmp_eq_u32 s48, 13
	s_nop 0
	v_writelane_b32 v246, s9, 51
	s_cselect_b64 s[8:9], -1, 0
	v_writelane_b32 v246, s8, 52
	s_cmp_eq_u32 s48, 12
	s_nop 0
	v_writelane_b32 v246, s9, 53
	s_cselect_b64 s[8:9], -1, 0
	v_writelane_b32 v246, s8, 54
	s_cmp_eq_u32 s48, 11
	s_nop 0
	v_writelane_b32 v246, s9, 55
	s_cselect_b64 s[8:9], -1, 0
	v_writelane_b32 v246, s8, 56
	s_cmp_eq_u32 s48, 10
	s_nop 0
	v_writelane_b32 v246, s9, 57
	s_cselect_b64 s[8:9], -1, 0
	v_writelane_b32 v246, s8, 58
	s_cmp_eq_u32 s48, 9
	s_nop 0
	v_writelane_b32 v246, s9, 59
	s_cselect_b64 s[8:9], -1, 0
	v_writelane_b32 v246, s8, 60
	s_cmp_eq_u32 s48, 8
	s_nop 0
	v_writelane_b32 v246, s9, 61
	s_cselect_b64 s[8:9], -1, 0
	v_writelane_b32 v246, s8, 62
	s_cmp_eq_u32 s48, 7
	s_nop 0
	v_writelane_b32 v246, s9, 63
	s_cselect_b64 s[8:9], -1, 0
	v_writelane_b32 v245, s8, 0
	s_cmp_eq_u32 s48, 6
	s_nop 0
	v_writelane_b32 v245, s9, 1
	s_cselect_b64 s[8:9], -1, 0
	v_writelane_b32 v245, s8, 2
	s_cmp_eq_u32 s48, 5
	s_nop 0
	v_writelane_b32 v245, s9, 3
	s_cselect_b64 s[8:9], -1, 0
	v_writelane_b32 v245, s8, 4
	s_cmp_eq_u32 s48, 4
	s_nop 0
	v_writelane_b32 v245, s9, 5
	s_cselect_b64 s[8:9], -1, 0
	v_writelane_b32 v245, s8, 6
	s_cmp_eq_u32 s48, 3
	s_nop 0
	v_writelane_b32 v245, s9, 7
	s_cselect_b64 s[8:9], -1, 0
	v_writelane_b32 v245, s8, 8
	s_cmp_eq_u32 s48, 2
	s_nop 0
	v_writelane_b32 v245, s9, 9
	s_cselect_b64 s[8:9], -1, 0
	v_writelane_b32 v245, s8, 10
	s_cmp_eq_u32 s48, 1
	s_nop 0
	v_writelane_b32 v245, s9, 11
	s_cselect_b64 s[8:9], -1, 0
	v_writelane_b32 v245, s8, 12
	s_cmp_eq_u32 s48, 0
	s_nop 0
	v_writelane_b32 v245, s9, 13
	s_cselect_b64 s[8:9], -1, 0
	s_lshl_b32 s1, s48, 8
	s_add_u32 s1, s12, s1
	v_writelane_b32 v245, s8, 14
	s_addc_u32 s5, s13, 0
	s_nop 0
	v_writelane_b32 v245, s9, 15
	s_add_u32 s8, s1, 0x1400
	s_addc_u32 s9, s5, 0
	v_writelane_b32 v245, s8, 16
	s_nop 1
	v_writelane_b32 v245, s9, 17
	s_add_u32 s8, s1, 0x2400
	s_addc_u32 s9, s5, 0
	v_writelane_b32 v245, s8, 18
	s_nop 1
	v_writelane_b32 v245, s9, 19
	s_add_u32 s8, s78, 0xfc03400
	s_addc_u32 s9, s79, 0
	v_writelane_b32 v245, s8, 20
	s_nop 1
	v_writelane_b32 v245, s9, 21
	s_add_u32 s8, s78, 0xfc03500
	s_addc_u32 s9, s79, 0
	v_writelane_b32 v245, s8, 22
	s_cmp_gt_i32 s3, 63
	s_cselect_b32 s1, 32, 0
	v_writelane_b32 v245, s9, 23
	s_add_u32 s5, s78, 0x1a00000
	v_writelane_b32 v245, s5, 24
	s_addc_u32 s5, s79, 0
	s_add_u32 s90, s78, 0x4200000
	s_addc_u32 s91, s79, 0
	s_cmp_lt_i32 s2, 32
	v_writelane_b32 v245, s5, 25
	s_cselect_b64 s[8:9], -1, 0
	s_lshl_b32 s5, s0, 2
	v_writelane_b32 v245, s8, 26
	s_cmp_ge_i32 s2, s1
	s_nop 0
	v_writelane_b32 v245, s9, 27
	s_cselect_b64 s[8:9], -1, 0
	v_writelane_b32 v245, s8, 28
	s_sub_i32 s10, s2, s1
	s_cmp_eq_u32 s3, 0x100
	s_cbranch_scc0 .Lrm_wb
	s_and_b32 s98, s2, 7
	s_lshl_b32 s98, s98, 6
	s_lshr_b32 s99, s2, 3
	s_sub_i32 s99, s99, 4
	s_add_i32 s10, s98, s99
; #define LAS __attribute__((address_space(3)))
; __device__ __forceinline__ int otid() { int t = threadIdx.x; asm volatile("" : "+v"(t)); return t; }
; __global__ void __launch_bounds__(512) hymba_fwd(Args a) {
;     ...
;             if (bx >= NKV) {
;                 const int wb = bx - NKV, WG = G - NKV;
;                 const int tid = otid();
;                 if (tid < 128) ((LAS float*)(lds + 68608))[tid] = (tid < 64) ? a.mqn[l * 64 + tid] : a.mkn[l * 64 + tid - 64];
;                 if (tid < 512) ((LAS float*)(lds + 106496))[tid] = ((const float*)(a.ws + WS_LB))[l * 512 + tid];
;                 __syncthreads();
;                 { PrepIn cur; int u = wb; moba_prep_load(a, tid, u < 512 ? u : 0, cur);
;                   for (; u < 512; u += WG) { PrepIn nxt; moba_prep_unit(a, l, lds, tid, u, cur, nxt, (u + WG < 512) ? u + WG : u); cur = nxt; } }
;                 { HIn cur; int u = (wb + 160) % WG;     hgrn_load<false>(a, tid, u < 1024 ? u : 0, cur);
;                   for (; u < 1024; u += WG) { HIn nxt; hgrn_stage1_unit(a, l, lds, tid, u, cur, nxt, (u + WG < 1024) ? u + WG : u); cur = nxt; } }
;     ...
;         if (IN(base + 3)) {
;             { const int tid = otid();
;               if (tid < 512) ((LAS float*)(lds + 106496))[tid] = ((const float*)(a.ws + WS_LB))[l * 512 + tid];
;               if (tid < 128) ((LAS float*)(lds + 106496 + 2048))[tid] = a.hon[l * 128 + tid];
;               __syncthreads();
;               HIn cur; int u = bx; hgrn_load<true>(a, tid, u < 1024 ? u : 0, cur);
;                 for (; u < 1024; u += G) { HIn nxt; hgrn_stage3_unit(a, l, lds, tid, u, cur, nxt, (u + G < 1024) ? u + G : u); cur = nxt; } }
.Lrm_wb:
	s_sub_i32 s17, s3, s1
	v_writelane_b32 v245, s9, 29
	s_add_u32 s8, s78, 0xfb00000
	s_addc_u32 s9, s79, 0
	v_writelane_b32 v245, s8, 30
	s_cmpk_lt_i32 s10, 0x200
	s_nop 0
	v_writelane_b32 v245, s9, 31
	s_cselect_b64 s[8:9], -1, 0
	v_writelane_b32 v245, s8, 32
	s_nop 1
	v_writelane_b32 v245, s9, 33
	s_and_b64 s[8:9], s[8:9], exec
	s_cselect_b32 s1, s10, 0
	s_ashr_i32 s8, s1, 6
	s_ashr_i32 s9, s8, 31
	s_and_b32 s6, s1, 7
	s_lshl_b64 s[12:13], s[8:9], 11
	s_lshl_b32 s1, s1, 5
	v_writelane_b32 v245, s12, 34
	s_and_b32 s14, s1, 0x700
	s_lshl_b32 s1, s6, 7
	v_writelane_b32 v245, s13, 35
	s_add_u32 s12, s84, s1
	s_addc_u32 s13, s85, 0
	s_lshl_b32 s1, s8, 3
	s_or_b32 s8, s1, s6
	s_ashr_i32 s9, s8, 31
	s_lshl_b64 s[8:9], s[8:9], 18
	v_writelane_b32 v245, s12, 36
	s_add_u32 s8, s33, s8
	s_addc_u32 s9, s20, s9
	v_writelane_b32 v245, s13, 37
	v_writelane_b32 v245, s8, 38
	s_mov_b64 s[12:13], 0x1000
	s_nop 0
	v_writelane_b32 v245, s9, 39
	s_add_u32 s8, s78, 0xf700000
	s_addc_u32 s9, s79, 0
	v_writelane_b32 v245, s8, 40
	s_add_u32 s1, s78, 0xf600000
	s_nop 0
	v_writelane_b32 v245, s9, 41
	v_writelane_b32 v245, s1, 42
	s_addc_u32 s1, s79, 0
	v_writelane_b32 v245, s1, 43
	s_add_i32 s1, s10, 0xa0
	v_writelane_b32 v245, s10, 44
	s_add_u32 s6, s78, 0xf620000
	v_writelane_b32 v245, s6, 45
	s_addc_u32 s6, s79, 0
	s_cmpk_lt_i32 s2, 0x200
	v_writelane_b32 v245, s6, 46
	s_cselect_b64 s[8:9], -1, 0
	v_writelane_b32 v245, s8, 47
	s_lshl_b32 s6, s2, 5
	s_and_b32 s6, s6, 0xe0
	v_writelane_b32 v245, s9, 48
	s_ashr_i32 s8, s2, 3
	s_add_i32 s6, s6, s8
	s_ashr_i32 s6, s6, 2
	v_writelane_b32 v245, s6, 49
	s_and_b32 s6, s8, 3
	v_writelane_b32 v245, s6, 50
	s_xor_b32 s6, s6, 7
	s_cmpk_lt_i32 s2, 0x100
	v_writelane_b32 v245, s6, 51
	s_cselect_b64 s[8:9], -1, 0
	v_writelane_b32 v245, s8, 52
	s_lshl_b32 s6, s2, 9
	s_nop 0
	v_writelane_b32 v245, s9, 53
	v_writelane_b32 v245, s6, 54
	s_lshl_b32 s6, s3, 9
	s_cmpk_lt_i32 s2, 0x400
	v_writelane_b32 v245, s6, 55
	s_cselect_b64 s[8:9], -1, 0
	v_writelane_b32 v245, s8, 56
	s_nop 1
	v_writelane_b32 v245, s9, 57
	s_and_b64 s[8:9], s[8:9], exec
	s_cselect_b32 s6, s2, 0
	s_cmp_eq_u32 s3, 0x100
	s_cbranch_scc0 .Lrm_s3a
	s_and_b32 s6, s2, 7
	s_lshl_b32 s6, s6, 7
	s_lshr_b32 s8, s2, 3
	s_or_b32 s6, s6, s8
.Lrm_s3a:
	s_ashr_i32 s8, s6, 7
	s_ashr_i32 s9, s8, 31
	s_lshl_b64 s[10:11], s[8:9], 11
	s_lshl_b32 s8, s6, 6
	s_and_b32 s8, s8, 0x7c0
	s_lshl_b32 s6, s6, 3
	s_or_b32 s10, s10, s8
	s_and_b32 s6, s6, 0x300
	v_writelane_b32 v245, s10, 58
	s_add_u32 s8, s84, s6
	s_addc_u32 s9, s85, 0
	v_writelane_b32 v245, s11, 59
	v_writelane_b32 v245, s8, 60
	s_add_u32 s6, s78, 0x1400000
	s_nop 0
	v_writelane_b32 v245, s9, 61
	v_writelane_b32 v245, s6, 62
	s_addc_u32 s6, s79, 0
	v_writelane_b32 v245, s6, 63
	s_lshl_b32 s6, s0, 5
	s_add_u32 s8, s86, 0x1000
	s_addc_u32 s9, s87, 0
	v_writelane_b32 v244, s8, 0
	s_mov_b64 s[86:87], 0x40000
	s_nop 0
	v_writelane_b32 v244, s9, 1
	v_readlane_b32 s8, v246, 0
	v_readlane_b32 s9, v246, 1
	s_cmp_gt_i32 s9, 6
	s_cselect_b64 s[8:9], -1, 0
	v_writelane_b32 v244, s8, 2
	s_cmp_lt_i32 s0, 0
	s_cselect_b32 s10, s25, 0xa0
	v_writelane_b32 v244, s9, 3
	s_movk_i32 s8, 0x3ff
	v_and_or_b32 v0, v0, s8, v178
	v_cmp_eq_u32_e64 s[8:9], 0, v0
	v_lshlrev_b32_e32 v0, 4, v178
	v_add_u32_e32 v0, 0, v0
	v_writelane_b32 v244, s8, 4
	v_add_u32_e32 v189, 0x20000, v0
	s_nop 0
	v_writelane_b32 v244, s9, 5
	v_cmp_eq_u32_e64 s[8:9], 0, v178
	s_nop 1
	v_writelane_b32 v244, s8, 6
	s_nop 1
	v_writelane_b32 v244, s9, 7
	s_mul_i32 s8, s0, 5
	s_mul_i32 s9, s0, 33
	s_mul_i32 s0, s0, s10
	s_cselect_b32 s10, s8, s5
	s_cselect_b32 s9, s9, s6
	s_add_i32 s0, s0, s4
	s_mul_hi_i32 s5, s0, 0x66666667
	s_lshr_b32 s6, s5, 31
	s_ashr_i32 s5, s5, 6
	s_add_i32 s5, s5, s6
	s_mul_i32 s8, s5, 0xa0
	s_sub_i32 s8, s0, s8
	s_bfe_u32 s0, s8, 0x3001c
	v_writelane_b32 v244, s14, 8
	s_add_i32 s11, s8, s0
	s_lshl_b32 s5, s5, 3
	v_writelane_b32 v244, s15, 9
	s_sext_i32_i16 s14, s11
	s_and_b32 s11, s11, 0xfff8
	s_sub_i32 s11, s8, s11
	s_sext_i32_i16 s11, s11
	s_add_i32 s18, s5, s11
	s_ashr_i32 s11, s14, 3
	s_add_i32 s10, s10, s4
	v_writelane_b32 v244, s11, 10
	s_ashr_i32 s11, s10, 31
	s_lshr_b32 s11, s11, 27
	s_add_i32 s11, s10, s11
	s_lshr_b32 s0, s14, 3
	s_ashr_i32 s14, s11, 5
	s_and_b32 s11, s11, 0xffe0
	s_sub_i32 s11, s10, s11
	s_bfe_i32 s10, s11, 0x80000
	s_bfe_u32 s10, s10, 0x3000c
	s_add_i32 s15, s11, s10
	s_bfe_i32 s10, s15, 0x80000
	s_and_b32 s15, s15, 0xf8
	s_sub_i32 s11, s11, s15
	s_lshl_b32 s14, s14, 3
	s_sext_i32_i16 s16, s10
	s_sext_i32_i8 s11, s11
	s_add_i32 s26, s14, s11
	s_ashr_i32 s11, s16, 3
	v_writelane_b32 v244, s11, 11
	s_mov_b32 s14, s26
	s_ashr_i32 s27, s26, 31
	v_writelane_b32 v244, s14, 12
	s_lshr_b32 s10, s16, 3
	s_add_i32 s4, s9, s4
	v_writelane_b32 v244, s15, 13
	s_lshl_b64 s[14:15], s[26:27], 19
	v_writelane_b32 v244, s14, 14
	s_bfe_i64 s[10:11], s[10:11], 0x100000
	s_ashr_i32 s9, s4, 31
	v_writelane_b32 v244, s15, 15
	s_lshl_b64 s[10:11], s[10:11], 19
	s_lshr_b32 s9, s9, 27
	v_writelane_b32 v244, s10, 16
	s_add_i32 s9, s4, s9
	s_sub_i32 s6, 64, s5
	v_writelane_b32 v244, s11, 17
	s_cmp_eq_u32 s3, 0x100
	s_cbranch_scc0 .Lrm_kv
	s_cmp_lt_u32 s2, 32
	s_cbranch_scc0 .Lrm_kv
	s_and_b32 s98, s2, 7
	s_lshr_b32 s99, s2, 3
	v_writelane_b32 v244, s99, 11
	v_writelane_b32 v244, s98, 12
	s_lshl_b32 s98, s98, 19
	s_lshl_b32 s99, s99, 19
	v_writelane_b32 v244, s98, 14
	v_writelane_b32 v244, s99, 16
	s_mov_b32 s98, 0
	s_nop 0
	v_writelane_b32 v244, s98, 15
	v_writelane_b32 v244, s98, 17
;     __device__ bool next(int i, Unit& u) const {
;     ...
;         int wgid = (int)L; { const int q = nwg / NXCD, r = nwg % NXCD, xcd = wgid % NXCD, off = wgid / NXCD; wgid = (xcd < r ? xcd * (q + 1) : r * (q + 1) + (xcd - r) * q) + off; }
;         const int nig = WGM * nN, gid = wgid / nig, fm = gid * WGM, gsz = (nM - fm) < WGM ? (nM - fm) : WGM;
;         u.pm = fm + ((wgid % nig) % gsz); u.pn = (wgid % nig) / gsz; return true;
; __global__ void __launch_bounds__(512) hymba_fwd(Args a) {
;     ...
;                 { HIn cur; int u = (wb + 160) % WG;     hgrn_load<false>(a, tid, u < 1024 ? u : 0, cur);
.Lrm_kv:
	s_ashr_i32 s10, s9, 5
	s_and_b32 s9, s9, 0xffe0
	s_sub_i32 s4, s4, s9
	s_bfe_i32 s9, s4, 0x80000
	s_bfe_u32 s9, s9, 0x3000c
	s_add_i32 s9, s4, s9
	s_bfe_i32 s11, s9, 0x80000
	s_and_b32 s9, s9, 0xf8
	s_sub_i32 s4, s4, s9
	s_lshl_b32 s10, s10, 3
	s_sext_i32_i8 s4, s4
	s_add_i32 s10, s10, s4
	s_sext_i32_i16 s11, s11
	s_mov_b32 s4, s10
	s_ashr_i32 s9, s11, 3
	v_writelane_b32 v244, s4, 18
	s_ashr_i32 s11, s10, 31
	s_min_i32 s6, s6, 8
	v_writelane_b32 v244, s5, 19
	s_mul_hi_i32 s4, s9, 0xc0000
	s_lshl_b64 s[10:11], s[10:11], 21
	v_writelane_b32 v244, s4, 20
	v_writelane_b32 v244, s9, 21
	s_mul_i32 s4, s9, 0xc0000
	s_add_u32 s10, s84, s10
	v_writelane_b32 v244, s4, 22
	s_addc_u32 s11, s85, s11
	s_add_u32 s14, s10, 0x100000
	v_writelane_b32 v244, s10, 23
	s_addc_u32 s15, s11, 0
	s_ashr_i32 s19, s18, 31
	v_writelane_b32 v244, s11, 24
	v_writelane_b32 v244, s14, 25
	s_mov_b32 s4, s18
	s_lshl_b64 s[10:11], s[18:19], 19
	v_writelane_b32 v244, s15, 26
	s_bfe_i64 s[14:15], s[0:1], 0x100000
	v_writelane_b32 v244, s4, 27
	s_lshl_b64 s[14:15], s[14:15], 19
	s_add_u32 s10, s88, s10
	v_writelane_b32 v244, s5, 28
	v_writelane_b32 v244, s14, 29
	s_addc_u32 s11, s89, s11
	s_movk_i32 s26, 0x1000
	v_writelane_b32 v244, s15, 30
	s_add_u32 s14, s10, 0x40000
	v_writelane_b32 v244, s10, 31
	s_addc_u32 s15, s11, 0
	s_abs_i32 s6, s6
	v_cvt_f32_u32_e32 v1, s6
	s_ashr_i32 s0, s8, 31
	s_abs_i32 s4, s8
	s_sub_i32 s8, 0, s6
	v_rcp_iflag_f32_e32 v1, v1
	v_writelane_b32 v244, s11, 32
	v_writelane_b32 v244, s14, 33
	s_movk_i32 s27, 0x120
	v_mul_f32_e32 v1, 0x4f7ffffe, v1
	v_cvt_u32_f32_e32 v1, v1
	v_writelane_b32 v244, s15, 34
	s_mov_b32 s10, 0
	v_readfirstlane_b32 s9, v1
	s_mul_i32 s8, s8, s9
	s_mul_hi_u32 s8, s9, s8
	s_add_i32 s9, s9, s8
	s_mul_hi_u32 s8, s4, s9
	s_mul_i32 s8, s8, s6
	s_sub_i32 s4, s4, s8
	s_sub_i32 s8, s4, s6
	s_cmp_ge_u32 s4, s6
	s_cselect_b32 s4, s8, s4
	s_sub_i32 s8, s4, s6
	s_cmp_ge_u32 s4, s6
	s_cselect_b32 s4, s8, s4
	s_xor_b32 s4, s4, s0
	s_sub_i32 s0, s4, s0
	s_abs_i32 s4, s17
	v_cvt_f32_u32_e32 v1, s4
	s_add_i32 s0, s5, s0
	s_sub_i32 s5, 0, s4
	v_writelane_b32 v244, s0, 35
	v_rcp_iflag_f32_e32 v1, v1
	s_ashr_i32 s0, s1, 31
	s_abs_i32 s1, s1
	v_writelane_b32 v244, s17, 36
	v_mul_f32_e32 v1, 0x4f7ffffe, v1
	v_cvt_u32_f32_e32 v1, v1
	s_nop 0
	v_readfirstlane_b32 s6, v1
	s_mul_i32 s5, s5, s6
	s_mul_hi_u32 s5, s6, s5
	s_add_i32 s6, s6, s5
	s_mul_hi_u32 s5, s1, s6
	s_mul_i32 s5, s5, s4
	s_sub_i32 s1, s1, s5
	s_sub_i32 s5, s1, s4
	s_cmp_ge_u32 s1, s4
	s_cselect_b32 s1, s5, s1
	s_sub_i32 s5, s1, s4
	s_cmp_ge_u32 s1, s4
	s_cselect_b32 s1, s5, s1
	s_xor_b32 s1, s1, s0
	s_sub_i32 s4, s1, s0
	s_cmp_eq_u32 s3, 0x100
	s_cbranch_scc0 .Lrm_s1a
	s_lshr_b32 s0, s2, 3
	s_add_i32 s0, s0, 16
	s_cmp_ge_u32 s0, 28
	s_cselect_b32 s1, 28, 0
	s_sub_i32 s0, s0, s1
	s_and_b32 s1, s2, 7
	s_lshl_b32 s1, s1, 7
	s_add_i32 s4, s1, s0
.Lrm_s1a:
	s_cmpk_lt_i32 s4, 0x400
	s_cselect_b64 s[0:1], -1, 0
	v_writelane_b32 v244, s0, 37
	v_mbcnt_lo_u32_b32 v1, -1, 0
	v_mbcnt_hi_u32_b32 v188, -1, v1
	v_writelane_b32 v244, s1, 38
	s_ashr_i32 s0, s4, 7
	s_ashr_i32 s1, s0, 31
	s_lshl_b64 s[8:9], s[0:1], 11
	s_lshl_b32 s0, s4, 6
	s_and_b32 s0, s0, 0x7c0
	s_or_b32 s8, s8, s0
	s_lshl_b32 s0, s4, 3
	v_writelane_b32 v244, s8, 39
	s_and_b32 s0, s0, 0x300
	s_add_u32 s0, s84, s0
	v_writelane_b32 v244, s9, 40
	v_writelane_b32 v244, s4, 41
	s_addc_u32 s1, s85, 0
	v_writelane_b32 v244, s0, 42
	s_add_i32 s4, 0, 0x23ff0
	s_nop 0
	v_writelane_b32 v244, s1, 43
	s_lshl_b32 s0, s2, 11
	v_writelane_b32 v244, s0, 44
	s_lshl_b32 s0, s3, 11
	v_writelane_b32 v244, s0, 45
	s_mov_b64 s[0:1], -1
	v_writelane_b32 v244, s0, 46
	s_nop 1
	v_writelane_b32 v244, s1, 47
	v_writelane_b32 v244, s4, 48
	s_add_i32 s4, 0, 0x23ff4
	v_writelane_b32 v244, s4, 49
	s_add_i32 s4, 0, 0x10400
	v_writelane_b32 v244, s4, 50
	s_add_i32 s4, 0, 0x13880
	v_writelane_b32 v244, s4, 51
	s_add_i32 s4, 0, 0x13884
	v_writelane_b32 v244, s4, 52
	s_add_i32 s4, 0, 0x11000
	v_writelane_b32 v244, s4, 53
	s_add_i32 s4, 0, 0x15400
	v_writelane_b32 v244, s4, 54
	s_add_i32 s4, 0, 0x19c00
	v_writelane_b32 v244, s4, 55
	v_writelane_b32 v244, s54, 56
	s_mov_b64 s[0:1], 0x80
	s_nop 0
	v_writelane_b32 v244, s55, 57
	v_writelane_b32 v244, s56, 58
	s_nop 1
	v_writelane_b32 v244, s57, 59
	s_branch .LBB0_156

; #define SEAM(k) do { if (IN(k) && IN((k) + 1)) { if (a.pad == 0x5eed) cg::this_grid().sync(); xcd_barrier(xbar); } } while (0)
; __global__ void __launch_bounds__(512) hymba_fwd(Args a) {
;     ...
;         SEAM(base + 1);
.LBB0_334:
	v_readlane_b32 s4, v244, 46
	v_readlane_b32 s5, v244, 47
	s_xor_b64 s[82:83], s[4:5], -1
	v_readlane_b32 s4, v244, 60
	v_readlane_b32 s8, v246, 0
	s_add_i32 s4, s4, 2
	v_readlane_b32 s9, v246, 1
	s_cmp_lt_i32 s4, s9
	s_cselect_b64 s[40:41], -1, 0
	s_and_b64 s[8:9], s[46:47], s[40:41]
	s_andn2_b64 vcc, exec, s[8:9]
	v_readlane_b32 s8, v246, 12
	v_readlane_b32 s9, v246, 13
	s_nop 1
	v_cndmask_b32_e64 v0, 0, 1, s[8:9]
	v_cmp_ne_u32_e64 s[96:97], 1, v0
	s_cbranch_vccnz .LBB0_396
	s_cmp_eq_u32 s3, 0x100
	s_cbranch_scc1 .Lbbsb
	s_and_b64 vcc, exec, s[96:97]
	s_cbranch_vccnz .LBB0_347
	s_barrier
	s_mov_b64 s[14:15], exec
	v_readlane_b32 s8, v244, 4
	v_readlane_b32 s9, v244, 5
	s_and_b64 s[8:9], s[14:15], s[8:9]
	s_mov_b64 exec, s[8:9]
	s_cbranch_execz .LBB0_346
	v_readlane_b32 s8, v246, 2
	v_readlane_b32 s9, v246, 3
	buffer_wbl2 sc1
	s_waitcnt vmcnt(0)
	s_load_dwordx2 s[16:17], s[8:9], 0x58
	s_mov_b64 s[18:19], exec
	v_mbcnt_lo_u32_b32 v1, s18, 0
	v_mbcnt_hi_u32_b32 v1, s19, v1
	v_cmp_eq_u32_e32 vcc, 0, v1
	s_waitcnt lgkmcnt(0)
	global_load_dword v0, v145, s[16:17] offset:40
	s_and_saveexec_b64 s[42:43], vcc
	s_cbranch_execz .LBB0_339
	s_bcnt1_i32_b64 s5, s[18:19]
	v_mov_b32_e32 v2, s5
	global_atomic_add v2, v145, v2, s[16:17] offset:32 sc0

; #define LAS __attribute__((address_space(3)))
; __device__ __forceinline__ void moba_prep_load(const Args& a, int tid, int u, PrepIn& r) {
;     const int b = u >> 6, j = (u >> 3) & 7, h = u & 7, tok = tid >> 1, half = tid & 1;
;     const size_t row = (size_t)b * SEQ + j * 256 + tok;
;     const bf16_t* p = (const bf16_t*)(a.ws + WS_PROJ) + row * NCOL + h * 64 + half * 32;
;     const bf16_t* pk = (const bf16_t*)(a.ws + WS_KC) + ((size_t)(b * 8 + h) * SEQ + j * 256 + tok) * 64 + half * 32;
; #pragma unroll
;     for (int c = 0; c < 4; ++c) { r.q[c] = *(const u32x4*)(p + CQA + c * 8); r.k[c] = *(const u32x4*)(pk + c * 8); }
;     const f32x4* rope = (const f32x4*)((const float*)(a.ws + WS_ROPE) + row * 16);
;     const f32x4 c0 = rope[0], c1 = rope[1], s0 = rope[2], s1 = rope[3];
;     r.cs[0] = c0.x; r.cs[1] = c0.y; r.cs[2] = c0.z; r.cs[3] = c0.w; r.cs[4] = c1.x; r.cs[5] = c1.y; r.cs[6] = c1.z; r.cs[7] = c1.w;
;     r.sn[0] = s0.x; r.sn[1] = s0.y; r.sn[2] = s0.z; r.sn[3] = s0.w; r.sn[4] = s1.x; r.sn[5] = s1.y; r.sn[6] = s1.z; r.sn[7] = s1.w;
; }
; __global__ void __launch_bounds__(512) hymba_fwd(Args a) {
;     ...
;                 if (tid < 128) ((LAS float*)(lds + 68608))[tid] = (tid < 64) ? a.mqn[l * 64 + tid] : a.mkn[l * 64 + tid - 64];
;                 if (tid < 512) ((LAS float*)(lds + 106496))[tid] = ((const float*)(a.ws + WS_LB))[l * 512 + tid];
;                 __syncthreads();
;                 { PrepIn cur; int u = wb; moba_prep_load(a, tid, u < 512 ? u : 0, cur);
;                   for (; u < 512; u += WG) { PrepIn nxt; moba_prep_unit(a, l, lds, tid, u, cur, nxt, (u + WG < 512) ? u + WG : u); cur = nxt; } }
;                 { HIn cur; int u = (wb + 160) % WG;     hgrn_load<false>(a, tid, u < 1024 ? u : 0, cur);
;                   for (; u < 1024; u += WG) { HIn nxt; hgrn_stage1_unit(a, l, lds, tid, u, cur, nxt, (u + WG < 1024) ? u + WG : u); cur = nxt; } }
.LBB0_424:
	s_or_b64 exec, exec, s[14:15]
	v_readlane_b32 s4, v245, 32
	v_readlane_b32 s5, v245, 33
	s_andn2_b64 vcc, exec, s[4:5]
	v_lshlrev_b32_e32 v124, 5, v96
	v_ashrrev_i32_e32 v97, 31, v96
	s_waitcnt lgkmcnt(0)
	s_barrier
	s_cbranch_vccnz .LBB0_435
	v_ashrrev_i32_e32 v98, 1, v96
	v_lshlrev_b32_e32 v196, 6, v96
	v_add_u32_e32 v196, 0x11000, v196
	v_and_b32_e32 v199, 63, v96
	v_lshrrev_b32_e32 v198, 6, v96
	v_lshlrev_b32_e32 v197, 4, v199
	v_lshl_or_b32 v197, v198, 12, v197
	v_add_u32_e32 v197, 0x11000, v197
	v_lshrrev_b32_e32 v201, 3, v199
	v_and_b32_e32 v200, 7, v199
	v_lshlrev_b32_e32 v200, 4, v200
	v_lshl_or_b32 v200, v201, 13, v200
	v_lshlrev_b32_e32 v199, 4, v199
	v_add_u32_e32 v201, 0x10000, v200
	v_add_u32_e32 v202, 0x20000, v200
	v_add_u32_e32 v203, 0x30000, v200
	v_readlane_b32 s4, v244, 8
	v_ashrrev_i32_e32 v99, 31, v98
	v_readlane_b32 s5, v244, 9
	v_and_b32_e32 v0, 32, v124
	v_lshlrev_b32_e32 v144, 1, v0
	v_lshl_add_u64 v[2:3], v[98:99], 0, s[4:5]
	v_readlane_b32 s4, v245, 34
	v_readlane_b32 s5, v245, 35
	v_and_b32_e32 v1, 1, v96
	v_lshlrev_b32_e32 v100, 5, v1
	v_lshl_add_u64 v[4:5], v[2:3], 0, s[4:5]
	v_readlane_b32 s4, v245, 40
	v_lshlrev_b64 v[6:7], 6, v[4:5]
	v_readlane_b32 s5, v245, 41
	v_lshlrev_b64 v[2:3], 7, v[2:3]
	v_cmp_eq_u32_e64 s[44:45], 0, v1
	v_lshl_add_u64 v[6:7], s[4:5], 0, v[6:7]
	v_readlane_b32 s4, v245, 38
	v_readlane_b32 s5, v245, 39
	global_load_dwordx4 v[48:51], v[6:7], off offset:48
	global_load_dwordx4 v[52:55], v[6:7], off offset:16
	global_load_dwordx4 v[56:59], v[6:7], off
	global_load_dwordx4 v[60:63], v[6:7], off offset:32
	v_lshl_add_u64 v[2:3], s[4:5], 0, v[2:3]
	v_lshl_add_u64 v[2:3], v[2:3], 0, v[144:145]
	v_readlane_b32 s4, v245, 36
	global_load_dwordx4 v[64:67], v[2:3], off offset:48
	global_load_dwordx4 v[68:71], v[2:3], off offset:32
	global_load_dwordx4 v[72:75], v[2:3], off offset:16
	global_load_dwordx4 v[76:79], v[2:3], off
	v_lshlrev_b64 v[2:3], 13, v[4:5]
	v_readlane_b32 s5, v245, 37
	v_lshrrev_b32_e32 v4, 5, v98
	v_cmp_gt_i32_e64 s[46:47], 64, v96
	v_lshl_add_u64 v[2:3], s[4:5], 0, v[2:3]
	v_lshl_add_u64 v[2:3], v[2:3], 0, v[144:145]
	global_load_dwordx4 v[80:83], v[2:3], off offset:48
	global_load_dwordx4 v[84:87], v[2:3], off offset:32
	global_load_dwordx4 v[88:91], v[2:3], off offset:16
	global_load_dwordx4 v[92:95], v[2:3], off
	s_add_i32 s4, 0, 0x10c00
	v_lshlrev_b32_e32 v2, 7, v1
	v_add_u32_e32 v125, s4, v2
	s_movk_i32 s4, 0x104
	v_add_u32_e32 v1, 0, v2
	v_mul_lo_u32 v2, v98, s4
	v_readlane_b32 s4, v244, 50
	v_and_b32_e32 v3, 63, v96
	v_lshlrev_b32_e32 v3, 2, v3
	v_lshl_add_u32 v126, v96, 2, s4
	s_movk_i32 s4, 0x2080
	v_mul_lo_u32 v4, v4, s4
	v_add3_u32 v127, v4, v3, 0
	v_lshlrev_b32_e32 v102, 1, v0
	v_add_u32_e32 v128, v1, v2
	v_readlane_b32 s5, v245, 44
	v_readlane_b32 s98, v244, 36
	s_movk_i32 s99, 0x200
	s_cmp_eq_u32 s3, 0x100
	s_cbranch_scc0 .Lrm_pp
	s_and_b32 s99, s2, 7
	s_add_i32 s99, s99, 1
	s_lshl_b32 s99, s99, 6
	s_mov_b32 s98, 28
.Lrm_pp:
	s_waitcnt vmcnt(11)
	v_mov_b32_e32 v105, v51
	s_waitcnt vmcnt(10)
	v_mov_b32_e32 v104, v55
	s_branch .LBB0_427

; #define LAS __attribute__((address_space(3)))
; __device__ __forceinline__ void moba_prep_load(const Args& a, int tid, int u, PrepIn& r) {
;     const int b = u >> 6, j = (u >> 3) & 7, h = u & 7, tok = tid >> 1, half = tid & 1;
;     const size_t row = (size_t)b * SEQ + j * 256 + tok;
;     const bf16_t* p = (const bf16_t*)(a.ws + WS_PROJ) + row * NCOL + h * 64 + half * 32;
;     const bf16_t* pk = (const bf16_t*)(a.ws + WS_KC) + ((size_t)(b * 8 + h) * SEQ + j * 256 + tok) * 64 + half * 32;
; #pragma unroll
;     for (int c = 0; c < 4; ++c) { r.q[c] = *(const u32x4*)(p + CQA + c * 8); r.k[c] = *(const u32x4*)(pk + c * 8); }
;     const f32x4* rope = (const f32x4*)((const float*)(a.ws + WS_ROPE) + row * 16);
;     const f32x4 c0 = rope[0], c1 = rope[1], s0 = rope[2], s1 = rope[3];
;     r.cs[0] = c0.x; r.cs[1] = c0.y; r.cs[2] = c0.z; r.cs[3] = c0.w; r.cs[4] = c1.x; r.cs[5] = c1.y; r.cs[6] = c1.z; r.cs[7] = c1.w;
;     r.sn[0] = s0.x; r.sn[1] = s0.y; r.sn[2] = s0.z; r.sn[3] = s0.w; r.sn[4] = s1.x; r.sn[5] = s1.y; r.sn[6] = s1.z; r.sn[7] = s1.w;
; }
; __device__ __forceinline__ void moba_prep_unit(const Args& a, int l, LAS unsigned char* lds, int tid, int u, const PrepIn& in, PrepIn& nxt, int unext) {
;     const int b = u >> 6, j = (u >> 3) & 7, h = u & 7, tok = tid >> 1, half = tid & 1;
;     bf16_t* proj = (bf16_t*)(a.ws + WS_PROJ);
;     const size_t row = (size_t)b * SEQ + j * 256 + tok;
;     LAS float* kt = (LAS float*)lds;
;     LAS float* part = (LAS float*)(lds + 66560);
;     float vq[32], vk[32];
; #pragma unroll
;     for (int c = 0; c < 4; ++c) { const u32x4 uq = in.q[c], uk = in.k[c];
;         vq[c * 8 + 0] = bflo(uq.x); vq[c * 8 + 1] = bfhi(uq.x); vq[c * 8 + 2] = bflo(uq.y); vq[c * 8 + 3] = bfhi(uq.y); vq[c * 8 + 4] = bflo(uq.z); vq[c * 8 + 5] = bfhi(uq.z); vq[c * 8 + 6] = bflo(uq.w); vq[c * 8 + 7] = bfhi(uq.w);
;         vk[c * 8 + 0] = bflo(uk.x); vk[c * 8 + 1] = bfhi(uk.x); vk[c * 8 + 2] = bflo(uk.y); vk[c * 8 + 3] = bfhi(uk.y); vk[c * 8 + 4] = bflo(uk.z); vk[c * 8 + 5] = bfhi(uk.z); vk[c * 8 + 6] = bflo(uk.w); vk[c * 8 + 7] = bfhi(uk.w); }
;     float cs[8], sn[8];
; #pragma unroll
;     for (int i = 0; i < 8; ++i) { cs[i] = in.cs[i]; sn[i] = in.sn[i]; }
;     asm volatile("" ::: "memory");
;     moba_prep_load(a, tid, unext, nxt);
; #pragma unroll
;     for (int which = 0; which < 2; ++which) {
.LBB0_427:
	s_mov_b32 s4, s98
	s_add_i32 s4, s5, s4
	s_cmp_ge_i32 s4, s99
	s_cselect_b64 s[40:41], -1, 0
	s_cmp_lt_i32 s4, s99
	s_cselect_b32 s6, s4, s5
	s_ashr_i32 s8, s6, 6
	s_and_b32 s14, s6, 7
	s_lshl_b32 s6, s6, 5
	s_ashr_i32 s9, s8, 31
	s_and_b32 s6, s6, 0x700
	s_lshl_b64 s[10:11], s[8:9], 11
	v_lshl_add_u64 v[0:1], s[6:7], 0, v[98:99]
	v_lshl_add_u64 v[2:3], v[0:1], 0, s[10:11]
	v_lshlrev_b64 v[4:5], 13, v[2:3]
	v_lshl_add_u64 v[4:5], s[84:85], 0, v[4:5]
	s_lshl_b32 s6, s14, 7
	v_lshl_add_u64 v[4:5], v[4:5], 0, s[6:7]
	s_lshl_b32 s6, s8, 3
	s_or_b32 s8, s6, s14
	s_ashr_i32 s9, s8, 31
	s_lshl_b64 s[8:9], s[8:9], 18
	s_add_u32 s8, s33, s8
	v_mov_b32_e32 v103, v145
	v_lshlrev_b64 v[0:1], 7, v[0:1]
	s_addc_u32 s9, s20, s9
	v_lshl_add_u64 v[4:5], v[4:5], 0, v[102:103]
	v_lshl_add_u64 v[0:1], s[8:9], 0, v[0:1]
	v_lshl_add_u64 v[0:1], v[0:1], 0, v[102:103]
	global_load_dwordx4 v[12:15], v[4:5], off offset:48
	global_load_dwordx4 v[16:19], v[4:5], off offset:32
	global_load_dwordx4 v[20:23], v[4:5], off offset:16
	global_load_dwordx4 v[24:27], v[4:5], off
	global_load_dwordx4 v[32:35], v[0:1], off offset:48
	global_load_dwordx4 v[36:39], v[0:1], off offset:32
	global_load_dwordx4 v[40:43], v[0:1], off offset:16
	global_load_dwordx4 v[44:47], v[0:1], off
	v_readlane_b32 s8, v245, 40
	v_lshlrev_b64 v[0:1], 6, v[2:3]
	v_readlane_b32 s9, v245, 41
	v_and_b32_e32 v103, 64, v188
	v_xor_b32_e32 v55, 1, v188
	v_lshl_add_u64 v[28:29], s[8:9], 0, v[0:1]
	global_load_dwordx4 v[0:3], v[28:29], off offset:48
	global_load_dwordx4 v[8:11], v[28:29], off offset:32
	global_load_dwordx4 v[4:7], v[28:29], off offset:16
	s_nop 0
	global_load_dwordx4 v[28:31], v[28:29], off
	v_add_u32_e32 v103, 64, v103
	v_cmp_lt_i32_e32 vcc, v55, v103
	s_waitcnt vmcnt(12)
	v_lshlrev_b32_e32 v120, 16, v92
	v_and_b32_e32 v121, 0xffff0000, v92
	v_cndmask_b32_e32 v55, v188, v55, vcc
	v_pk_mul_f32 v[122:123], v[120:121], v[120:121]
	v_lshlrev_b32_e32 v164, 16, v93
	v_and_b32_e32 v165, 0xffff0000, v93
	v_lshlrev_b32_e32 v103, 2, v55
	v_lshlrev_b32_e32 v162, 16, v88
	v_and_b32_e32 v163, 0xffff0000, v88
	v_lshlrev_b32_e32 v166, 16, v89
	v_and_b32_e32 v167, 0xffff0000, v89
	v_pk_mul_f32 v[88:89], v[164:165], v[164:165]
	v_add_f32_e32 v55, v122, v123
	v_lshlrev_b32_e32 v168, 16, v94
	v_and_b32_e32 v169, 0xffff0000, v94
	v_add_f32_e32 v55, v88, v55
	v_lshlrev_b32_e32 v51, 16, v95
	v_and_b32_e32 v159, 0xffff0000, v95
	v_pk_mul_f32 v[94:95], v[168:169], v[168:169]
	v_add_f32_e32 v55, v89, v55
	v_add_f32_e32 v55, v94, v55
	v_and_b32_e32 v158, 0xffff0000, v91
	v_add_f32_e32 v55, v95, v55
	v_pk_mul_f32 v[118:119], v[158:159], v[158:159]
	v_fmac_f32_e32 v55, v51, v51
	v_pk_mul_f32 v[138:139], v[162:163], v[162:163]
	v_add_f32_e32 v55, v119, v55
	v_add_f32_e32 v55, v138, v55
	v_pk_mul_f32 v[92:93], v[166:167], v[166:167]
	v_add_f32_e32 v55, v139, v55
	v_lshlrev_b32_e32 v170, 16, v90
	v_and_b32_e32 v171, 0xffff0000, v90
	v_add_f32_e32 v55, v92, v55
	v_pk_mul_f32 v[140:141], v[170:171], v[170:171]
	v_add_f32_e32 v55, v93, v55
	v_add_f32_e32 v55, v140, v55
	v_lshlrev_b32_e32 v173, 16, v84
	v_lshlrev_b32_e32 v172, 16, v91
	v_add_f32_e32 v55, v141, v55
	v_pk_mul_f32 v[88:89], v[172:173], v[172:173]
	v_and_b32_e32 v174, 0xffff0000, v84
	v_add_f32_e32 v55, v88, v55
	v_add_f32_e32 v55, v118, v55
	v_lshlrev_b32_e32 v175, 16, v85
	v_add_f32_e32 v55, v89, v55
	v_pk_mul_f32 v[118:119], v[174:175], v[174:175]
	v_and_b32_e32 v176, 0xffff0000, v85
	v_add_f32_e32 v55, v118, v55
	v_lshlrev_b32_e32 v177, 16, v86
	v_add_f32_e32 v55, v119, v55
	v_pk_mul_f32 v[84:85], v[176:177], v[176:177]
	v_and_b32_e32 v180, 0xffff0000, v86
	v_add_f32_e32 v55, v84, v55
	v_lshlrev_b32_e32 v181, 16, v87
	v_add_f32_e32 v55, v85, v55
	v_pk_mul_f32 v[84:85], v[180:181], v[180:181]
	v_and_b32_e32 v86, 0xffff0000, v87
	v_add_f32_e32 v55, v84, v55
	v_lshlrev_b32_e32 v87, 16, v80
	v_add_f32_e32 v55, v85, v55
	v_pk_mul_f32 v[84:85], v[86:87], v[86:87]
	v_lshlrev_b32_e32 v183, 16, v81
	v_add_f32_e32 v55, v84, v55
	v_and_b32_e32 v116, 0xffff0000, v81
	v_add_f32_e32 v55, v85, v55
	v_and_b32_e32 v182, 0xffff0000, v80
	v_mov_b32_e32 v117, v183
	v_pk_mul_f32 v[80:81], v[116:117], v[116:117]
	v_fmac_f32_e32 v55, v182, v182
	v_and_b32_e32 v142, 0xffff0000, v82
	v_lshlrev_b32_e32 v143, 16, v82
	v_add_f32_e32 v55, v81, v55
	v_pk_mul_f32 v[114:115], v[142:143], v[142:143]
	v_add_f32_e32 v55, v80, v55
	v_and_b32_e32 v156, 0xffff0000, v83
	v_lshlrev_b32_e32 v157, 16, v83
	v_add_f32_e32 v55, v115, v55
	v_pk_mul_f32 v[82:83], v[156:157], v[156:157]
	v_add_f32_e32 v55, v114, v55
	v_add_f32_e32 v55, v83, v55
	v_add_f32_e32 v55, v82, v55
	ds_bpermute_b32 v114, v103, v55
	ds_read_b128 v[106:109], v125 offset:32
	ds_read_b128 v[130:133], v125 offset:48
	ds_read_b128 v[110:113], v125
	ds_read_b128 v[134:137], v125 offset:16
	ds_read_b128 v[92:95], v125 offset:64
	ds_read_b128 v[88:91], v125 offset:80
	ds_read_b128 v[82:85], v125 offset:96
	ds_read_b128 v[138:141], v125 offset:112
	s_waitcnt lgkmcnt(8)
; #define LAS __attribute__((address_space(3)))
; __device__ __forceinline__ float frsq(float x) { return __builtin_amdgcn_rsqf(x); }
; __device__ __forceinline__ void moba_prep_unit(const Args& a, int l, LAS unsigned char* lds, int tid, int u, const PrepIn& in, PrepIn& nxt, int unext) {
;     ...
;         ss += __shfl_xor(ss, 1);
;         const float r = frsq(ss * (1.f / 64.f) + EPS) * (which ? 1.f : 0.125f * LOG2E);
; #pragma unroll
;         for (int c = 0; c < 8; ++c) { const f32x4 gg = *(const LAS f32x4*)(g + c * 4); v[c * 4] *= r * gg.x; v[c * 4 + 1] *= r * gg.y; v[c * 4 + 2] *= r * gg.z; v[c * 4 + 3] *= r * gg.w; }
;         if (half == 0) {
; #pragma unroll
;             for (int i = 0; i < 8; ++i) { const float x1 = v[i], x2 = v[8 + i]; v[i] = x1 * cs[i] - x2 * sn[i]; v[8 + i] = x2 * cs[i] + x1 * sn[i]; }
	v_add_f32_e32 v55, v55, v114
	v_fmamk_f32 v55, v55, 0x3c800000, v186
	v_rsq_f32_e32 v55, v55
	s_waitcnt lgkmcnt(2)
	v_pk_mov_b32 v[80:81], v[94:95], v[88:89] op_sel:[1,0]
	v_mov_b32_e32 v192, v89
	v_mov_b32_e32 v160, v133
	v_mul_f32_e32 v144, 0x3e38aa3b, v55
	v_pk_mul_f32 v[88:89], v[110:111], v[144:145] op_sel_hi:[1,0]
	v_mov_b32_e32 v161, v137
	v_pk_mul_f32 v[122:123], v[88:89], v[120:121]
	v_pk_mul_f32 v[88:89], v[112:113], v[144:145] op_sel_hi:[1,0]
	v_mov_b32_e32 v133, v92
	v_pk_mul_f32 v[120:121], v[88:89], v[164:165]
	v_pk_mul_f32 v[88:89], v[134:135], v[144:145] op_sel_hi:[1,0]
	v_mov_b32_e32 v92, v93
	v_mov_b32_e32 v93, v94
	v_mov_b32_e32 v193, v90
	v_pk_mul_f32 v[118:119], v[88:89], v[168:169]
	v_pk_mul_f32 v[88:89], v[160:161], v[144:145] op_sel_hi:[1,0]
	v_pk_mul_f32 v[80:81], v[144:145], v[80:81] op_sel_hi:[0,1]
	s_waitcnt lgkmcnt(1)
	v_pk_mov_b32 v[194:195], v[90:91], v[82:83] op_sel:[1,0]
	v_pk_mul_f32 v[114:115], v[88:89], v[158:159]
	v_pk_mul_f32 v[88:89], v[106:107], v[144:145] op_sel_hi:[1,0]
	v_pk_mul_f32 v[90:91], v[144:145], v[92:93] op_sel_hi:[0,1]
	v_pk_mul_f32 v[92:93], v[80:81], v[176:177]
	v_pk_mul_f32 v[80:81], v[144:145], v[192:193] op_sel_hi:[0,1]
	v_pk_mul_f32 v[94:95], v[88:89], v[162:163]
	v_pk_mul_f32 v[88:89], v[108:109], v[144:145] op_sel_hi:[1,0]
	v_pk_mul_f32 v[106:107], v[80:81], v[180:181]
	v_pk_mul_f32 v[80:81], v[144:145], v[194:195] op_sel_hi:[0,1]
	v_mul_f32_e32 v55, v136, v144
	v_pk_mul_f32 v[108:109], v[88:89], v[166:167]
	v_pk_mul_f32 v[88:89], v[130:131], v[144:145] op_sel_hi:[1,0]
	v_pk_mul_f32 v[80:81], v[80:81], v[86:87]
	v_mov_b32_e32 v82, v83
	v_mov_b32_e32 v83, v84
	s_waitcnt lgkmcnt(0)
	v_pk_mov_b32 v[84:85], v[84:85], v[138:139] op_sel:[1,0]
	v_mov_b32_e32 v86, v139
	v_mov_b32_e32 v87, v140
	v_mul_f32_e32 v112, v55, v51
	v_pk_mul_f32 v[110:111], v[88:89], v[170:171]
	v_pk_mul_f32 v[88:89], v[132:133], v[144:145] op_sel_hi:[1,0]
	v_pk_mul_f32 v[82:83], v[144:145], v[82:83] op_sel_hi:[0,1]
	v_pk_mul_f32 v[84:85], v[144:145], v[84:85] op_sel_hi:[0,1]
	v_mov_b32_e32 v117, v143
	v_pk_mul_f32 v[86:87], v[144:145], v[86:87] op_sel_hi:[0,1]
	v_mov_b32_e32 v143, v157
	v_mul_f32_e32 v51, v144, v141
	v_pk_mul_f32 v[88:89], v[88:89], v[172:173]
	v_pk_mul_f32 v[90:91], v[90:91], v[174:175]
	v_pk_mul_f32 v[82:83], v[82:83], v[182:183]
	v_pk_mul_f32 v[84:85], v[84:85], v[116:117]
	v_pk_mul_f32 v[86:87], v[86:87], v[142:143]
	v_mul_f32_e32 v116, v51, v156
	s_and_saveexec_b64 s[14:15], s[44:45]
	s_cbranch_execz .LBB0_429
	v_pk_mul_f32 v[130:131], v[60:61], v[94:95]
	v_mov_b32_e32 v113, v115
	v_pk_fma_f32 v[130:131], v[56:57], v[122:123], v[130:131] neg_lo:[0,0,1] neg_hi:[0,0,1]
	v_pk_mul_f32 v[122:123], v[60:61], v[122:123]
	v_mov_b32_e32 v51, v105
	v_pk_fma_f32 v[94:95], v[56:57], v[94:95], v[122:123]
	v_pk_mul_f32 v[122:123], v[62:63], v[108:109]
	v_mov_b32_e32 v55, v104
	v_pk_fma_f32 v[132:133], v[58:59], v[120:121], v[122:123] neg_lo:[0,0,1] neg_hi:[0,0,1]
	v_pk_mul_f32 v[120:121], v[62:63], v[120:121]
	v_mov_b32_e32 v122, v88
	v_pk_fma_f32 v[108:109], v[58:59], v[108:109], v[120:121]
	v_pk_mul_f32 v[120:121], v[48:49], v[110:111]
	v_mov_b32_e32 v123, v114
	v_pk_fma_f32 v[134:135], v[52:53], v[118:119], v[120:121] neg_lo:[0,0,1] neg_hi:[0,0,1]
	v_pk_mul_f32 v[118:119], v[48:49], v[118:119]
	v_pk_mul_f32 v[114:115], v[104:105], v[114:115]
	v_pk_fma_f32 v[110:111], v[52:53], v[110:111], v[118:119]
	v_mul_f32_e32 v118, v54, v88
	v_mul_f32_e32 v120, v50, v112
	v_pk_mul_f32 v[122:123], v[50:51], v[122:123]
	v_mov_b32_e32 v119, v114
	v_mov_b32_e32 v121, v115
	v_pk_fma_f32 v[112:113], v[54:55], v[112:113], v[122:123] neg_lo:[0,0,1] neg_hi:[0,0,1]
	v_pk_add_f32 v[136:137], v[118:119], v[120:121]
	v_mov_b32_e32 v122, v130
	v_mov_b32_e32 v123, v131
	v_mov_b32_e32 v120, v132
	v_mov_b32_e32 v121, v133
	v_mov_b32_e32 v118, v134
	v_mov_b32_e32 v119, v135
	v_mov_b32_e32 v115, v113
	v_mov_b32_e32 v88, v136
	v_mov_b32_e32 v114, v137

; template <bool NEEDQ>
; __device__ __forceinline__ void hgrn_load(const Args& a, int tid, int u, HIn& r) {
;     const int bh = u >> 5, c = u & 31, b = bh >> 2, hh = bh & 3; const size_t row0 = (size_t)b * SEQ + c * 64;
; #pragma unroll
;     for (int ii = 0; ii < 2; ++ii) { const int cid = tid + 512 * ii, t = cid >> 4, d0 = (cid & 15) * 8;
;         const bf16_t* p = (const bf16_t*)(a.ws + WS_PROJ) + (row0 + t) * NCOL + hh * 128 + d0;
;         r.f[ii] = *(const u32x4*)(p + CFH); r.v[ii] = *(const u32x4*)(p + CIH); if (NEEDQ) r.q[ii] = *(const u32x4*)(p + CQH); }
; }
; __global__ void __launch_bounds__(512) hymba_fwd(Args a) {
;     ...
;                 { HIn cur; int u = (wb + 160) % WG;     hgrn_load<false>(a, tid, u < 1024 ? u : 0, cur);
;                   for (; u < 1024; u += WG) { HIn nxt; hgrn_stage1_unit(a, l, lds, tid, u, cur, nxt, (u + WG < 1024) ? u + WG : u); cur = nxt; } }
.LBB0_435:
	v_readlane_b32 s4, v244, 37
	v_readlane_b32 s5, v244, 38
	s_andn2_b64 vcc, exec, s[4:5]
	s_cbranch_vccnz .LBB0_448
	v_lshlrev_b32_e32 v0, 3, v96
	v_and_b32_e32 v16, 0x78, v0
	v_add_u32_e32 v0, 0x200, v96
	v_ashrrev_i32_e32 v34, 4, v0
	v_readlane_b32 s4, v244, 39
	v_ashrrev_i32_e32 v35, 31, v34
	v_readlane_b32 s5, v244, 40
	v_readlane_b32 s8, v244, 42
	v_readlane_b32 s9, v244, 43
	v_lshl_add_u64 v[0:1], s[4:5], 0, v[34:35]
	v_lshlrev_b64 v[0:1], 13, v[0:1]
	v_lshl_add_u64 v[0:1], s[8:9], 0, v[0:1]
	v_lshlrev_b32_e32 v144, 1, v16
	v_lshl_add_u64 v[0:1], v[0:1], 0, v[144:145]
	v_ashrrev_i32_e32 v32, 4, v96
	v_add_co_u32_e32 v4, vcc, s26, v0
	v_ashrrev_i32_e32 v33, 31, v32
	s_nop 0
	v_addc_co_u32_e32 v5, vcc, 0, v1, vcc
	global_load_dwordx4 v[0:3], v[4:5], off offset:3072
	global_load_dwordx4 v[8:11], v[4:5], off offset:2048
	v_lshl_add_u64 v[4:5], s[4:5], 0, v[32:33]
	v_lshlrev_b64 v[4:5], 13, v[4:5]
	v_lshl_add_u64 v[4:5], s[8:9], 0, v[4:5]
	v_lshl_add_u64 v[4:5], v[4:5], 0, v[144:145]
	v_add_co_u32_e32 v12, vcc, s26, v4
	s_add_i32 s4, 0, 0x1a000
	s_nop 0
	v_addc_co_u32_e32 v13, vcc, 0, v5, vcc
	global_load_dwordx4 v[4:7], v[12:13], off offset:3072
	s_nop 0
	global_load_dwordx4 v[12:15], v[12:13], off offset:2048
	v_lshlrev_b32_e32 v17, 2, v16
	v_add_u32_e32 v64, s4, v17
	v_add_u32_e32 v65, 0, v17
	v_and_b32_e32 v17, 0xfffffe00, v124
	v_add_u32_e32 v66, v65, v17
	v_and_b32_e32 v17, 0x7f, v96
	v_ashrrev_i32_e32 v18, 7, v96
	v_lshl_add_u32 v67, v17, 2, 0
	v_and_b32_e32 v17, 15, v96
	v_lshl_add_u32 v68, v18, 13, v67
	v_cmp_lt_i32_e64 s[44:45], 0, v18
	v_cmp_lt_i32_e64 s[46:47], 1, v18
	v_cmp_lt_i32_e64 s[48:49], 2, v18
	v_lshrrev_b32_e32 v18, 2, v96
	v_lshlrev_b32_e32 v24, 3, v17
	v_bfe_u32 v25, v96, 2, 4
	v_sub_u32_e32 v19, v65, v144
	v_lshlrev_b32_e32 v20, 9, v32
	v_mul_lo_u32 v21, v32, s27
	v_lshlrev_b32_e32 v22, 9, v34
	v_mul_lo_u32 v23, v34, s27
	v_and_b32_e32 v18, 12, v18
	v_and_b32_e32 v69, 24, v24
	v_mul_u32_u24_e32 v71, 0x120, v25
	v_mad_u32_u24 v72, v25, s27, 0
	v_or_b32_e32 v25, 0x60, v24
	v_or_b32_e32 v24, 0xe0, v24
	v_add_u32_e32 v70, 0, v69
	v_lshlrev_b32_e32 v73, 3, v17
	v_lshlrev_b32_e32 v144, 1, v16
	v_add_u32_e32 v74, v65, v20
	v_add_u32_e32 v75, v19, v21
	v_add_u32_e32 v76, v65, v22
	v_add_u32_e32 v77, v19, v23
	v_add_u32_e32 v78, v72, v25
	v_add_u32_e32 v79, v72, v24
	v_and_b32_e32 v36, 4, v18
	v_and_b32_e32 v25, 8, v18
	v_lshlrev_b32_e32 v36, 1, v36
	v_lshl_or_b32 v36, v25, 5, v36
	v_readlane_b32 s8, v244, 41
	v_readlane_b32 s98, v244, 36
	s_movk_i32 s99, 0x400
	s_cmp_eq_u32 s3, 0x100
	s_cbranch_scc0 .Lrm_s1
	s_and_b32 s99, s2, 7
	s_add_i32 s99, s99, 1
	s_lshl_b32 s99, s99, 7
	s_mov_b32 s98, 28
.Lrm_s1:
	s_branch .LBB0_438

; #define LAS __attribute__((address_space(3)))
; __device__ __forceinline__ float bflo(unsigned u) { return __uint_as_float(u << 16); }
; __device__ __forceinline__ float bfhi(unsigned u) { return __uint_as_float(u & 0xffff0000u); }
; __device__ __forceinline__ float sigm(float x) { return frcp(1.f + fexp(-x)); }
; __device__ __forceinline__ void hgrn_stepA(const Args& a, int l, LAS unsigned char* lds, int tid, int hh, const HIn& in, float (&kf)[16]) {
;     LAS float* LF = (LAS float*)lds;
;     LAS float* PT = (LAS float*)(lds + 32768);
; #pragma unroll
;     for (int ii = 0; ii < 2; ++ii) {
;         const int cid = tid + 512 * ii, t = cid >> 4, d0 = (cid & 15) * 8;
;         const u32x4 u = in.f[ii];
;         float fl[8] = {bflo(u.x), bfhi(u.x), bflo(u.y), bfhi(u.y), bflo(u.z), bfhi(u.z), bflo(u.w), bfhi(u.w)};
;         float lf[8];
;         const LAS float* LB = (const LAS float*)(lds + 106496) + hh * 128 + d0; const f32x4 lb0 = *(const LAS f32x4*)LB, lb1 = *(const LAS f32x4*)(LB + 4);
;         const float lbv[8] = {lb0.x, lb0.y, lb0.z, lb0.w, lb1.x, lb1.y, lb1.z, lb1.w};
; #pragma unroll
;         for (int i = 0; i < 8; ++i) { const float lb = lbv[i]; const float sg = sigm(fl[i]);
;             const float f = lb + (1.f - lb) * sg; lf[i] = __logf(f); kf[ii * 8 + i] = (1.f - lb) * (1.f - sg); }
;         *(LAS f32x4*)(LF + t * 128 + d0) = (f32x4){lf[0], lf[1], lf[2], lf[3]}; *(LAS f32x4*)(LF + t * 128 + d0 + 4) = (f32x4){lf[4], lf[5], lf[6], lf[7]};
; __device__ __forceinline__ void hgrn_stage1_unit(const Args& a, int l, LAS unsigned char* lds, int tid, int u, const HIn& in, HIn& nxt, int unext) {
;     const int lane = tid & 63, w = __builtin_amdgcn_readfirstlane(tid >> 6), fr = lane & 15, fq = lane >> 4;
;     const int bh = u >> 5, c = u & 31, hh = bh & 3;
;     LAS float* LF = (LAS float*)lds;
;     LAS unsigned char* KN = lds + 34816;
;     LAS unsigned char* VN = lds + 34816 + 18432;
;     float kf[16];
;     hgrn_stepA(a, l, lds, tid, hh, in, kf);
;     hgrn_load<false>(a, tid, unext, nxt);
.LBB0_438:
	s_mov_b32 s4, s98
	s_add_i32 s4, s8, s4
	s_cmp_ge_i32 s4, s99
	s_waitcnt vmcnt(0)
	v_lshlrev_b32_e32 v21, 16, v12
	s_cselect_b64 s[52:53], -1, 0
	s_cmp_lt_i32 s4, s99
	v_mul_f32_e32 v21, 0xbfb8aa3b, v21
	s_cselect_b32 s6, s4, s8
	s_ashr_i32 s40, s8, 5
	v_exp_f32_e32 v21, v21
	s_lshl_b32 s9, s40, 9
	s_and_b32 s9, s9, 0x600
	v_add_u32_e32 v20, s9, v64
	v_and_b32_e32 v22, 0xffff0000, v12
	v_lshlrev_b32_e32 v23, 16, v13
	v_and_b32_e32 v28, 0xffff0000, v13
	v_lshlrev_b32_e32 v37, 16, v14
	v_and_b32_e32 v38, 0xffff0000, v14
	v_lshlrev_b32_e32 v42, 16, v15
	v_and_b32_e32 v43, 0xffff0000, v15
	ds_read_b128 v[16:19], v20
	ds_read_b128 v[12:15], v20 offset:16
	v_add_f32_e32 v21, 1.0, v21
	v_rcp_f32_e32 v26, v21
	v_mul_f32_e32 v21, 0xbfb8aa3b, v22
	v_exp_f32_e32 v21, v21
	s_waitcnt lgkmcnt(1)
	v_pk_add_f32 v[24:25], v[16:17], 1.0 op_sel_hi:[1,0] neg_lo:[1,0] neg_hi:[1,0]
	v_and_b32_e32 v22, 0xffff0000, v10
	v_fma_f32 v16, v26, v24, v16
	v_add_f32_e32 v21, 1.0, v21
	v_cmp_gt_f32_e32 vcc, s28, v16
	v_rcp_f32_e32 v27, v21
	s_ashr_i32 s10, s6, 7
	v_cndmask_b32_e64 v21, 0, 32, vcc
	v_ldexp_f32 v16, v16, v21
	v_log_f32_e32 v16, v16
	v_fma_f32 v17, v27, v25, v17
	s_ashr_i32 s11, s10, 31
	s_lshl_b32 s9, s6, 6
	v_mul_f32_e32 v21, 0x3f317217, v16
	v_fma_f32 v21, v16, s29, -v21
	v_fmac_f32_e32 v21, 0x3377d1cf, v16
	v_fmac_f32_e32 v21, 0x3f317217, v16
	v_cmp_lt_f32_e64 s[50:51], |v16|, s30
	s_lshl_b64 s[10:11], s[10:11], 11
	s_and_b32 s9, s9, 0x7c0
	v_cndmask_b32_e64 v16, v16, v21, s[50:51]
	v_cndmask_b32_e32 v21, 0, v190, vcc
	v_cmp_gt_f32_e32 vcc, s28, v17
	v_sub_f32_e32 v16, v16, v21
	s_or_b32 s10, s10, s9
	v_cndmask_b32_e64 v21, 0, 32, vcc
	v_ldexp_f32 v17, v17, v21
	v_log_f32_e32 v17, v17
	s_lshl_b32 s6, s6, 3
	s_and_b32 s6, s6, 0x300
	v_readfirstlane_b32 s5, v96
	v_mul_f32_e32 v21, 0x3f317217, v17
	v_fma_f32 v21, v17, s29, -v21
	v_fmac_f32_e32 v21, 0x3377d1cf, v17
	v_fmac_f32_e32 v21, 0x3f317217, v17
	v_cmp_lt_f32_e64 s[50:51], |v17|, s30
	v_mov_b32_e32 v93, 0
	s_nop 0
	v_cndmask_b32_e64 v17, v17, v21, s[50:51]
	v_cndmask_b32_e32 v21, 0, v190, vcc
	v_sub_f32_e32 v17, v17, v21
	v_mul_f32_e32 v21, 0xbfb8aa3b, v23
	v_exp_f32_e32 v21, v21
	v_lshlrev_b32_e32 v23, 16, v11
	v_add_f32_e32 v21, 1.0, v21
	v_rcp_f32_e32 v30, v21
	v_mul_f32_e32 v21, 0xbfb8aa3b, v28
	v_exp_f32_e32 v21, v21
	v_pk_add_f32 v[28:29], v[18:19], 1.0 op_sel_hi:[1,0] neg_lo:[1,0] neg_hi:[1,0]
	v_add_f32_e32 v21, 1.0, v21
	v_fma_f32 v18, v30, v28, v18
	v_cmp_gt_f32_e32 vcc, s28, v18
	v_rcp_f32_e32 v31, v21
	s_nop 0
	v_cndmask_b32_e64 v21, 0, 32, vcc
	v_ldexp_f32 v18, v18, v21
	v_log_f32_e32 v18, v18
	v_fmac_f32_e32 v19, v31, v29
	v_mul_f32_e32 v21, 0x3f317217, v18
	v_fma_f32 v21, v18, s29, -v21
	v_fmac_f32_e32 v21, 0x3377d1cf, v18
	v_fmac_f32_e32 v21, 0x3f317217, v18
	v_cmp_lt_f32_e64 s[50:51], |v18|, s30
	s_nop 1
	v_cndmask_b32_e64 v18, v18, v21, s[50:51]
	v_cndmask_b32_e32 v21, 0, v190, vcc
	v_cmp_gt_f32_e32 vcc, s28, v19
	v_sub_f32_e32 v18, v18, v21
	s_nop 0
	v_cndmask_b32_e64 v21, 0, 32, vcc
	v_ldexp_f32 v19, v19, v21
	v_log_f32_e32 v19, v19
	s_nop 0
	v_mul_f32_e32 v21, 0x3f317217, v19
	v_fma_f32 v21, v19, s29, -v21
	v_fmac_f32_e32 v21, 0x3377d1cf, v19
	v_fmac_f32_e32 v21, 0x3f317217, v19
	v_cmp_lt_f32_e64 s[50:51], |v19|, s30
	s_nop 1
	v_cndmask_b32_e64 v19, v19, v21, s[50:51]
	v_cndmask_b32_e32 v21, 0, v190, vcc
	v_sub_f32_e32 v19, v19, v21
	v_mul_f32_e32 v21, 0xbfb8aa3b, v37
	v_exp_f32_e32 v21, v21
	v_and_b32_e32 v37, 0xffff0000, v11
	v_add_f32_e32 v21, 1.0, v21
	v_rcp_f32_e32 v40, v21
	v_mul_f32_e32 v21, 0xbfb8aa3b, v38
	v_exp_f32_e32 v21, v21
	s_waitcnt lgkmcnt(0)
	v_pk_add_f32 v[38:39], v[12:13], 1.0 op_sel_hi:[1,0] neg_lo:[1,0] neg_hi:[1,0]
	v_add_f32_e32 v21, 1.0, v21
	v_fma_f32 v12, v40, v38, v12
	v_cmp_gt_f32_e32 vcc, s28, v12
	v_rcp_f32_e32 v41, v21
	s_nop 0
	v_cndmask_b32_e64 v21, 0, 32, vcc
	v_ldexp_f32 v12, v12, v21
	v_log_f32_e32 v12, v12
	v_fma_f32 v13, v41, v39, v13
	v_mul_f32_e32 v21, 0x3f317217, v12
	v_fma_f32 v21, v12, s29, -v21
	v_fmac_f32_e32 v21, 0x3377d1cf, v12
	v_fmac_f32_e32 v21, 0x3f317217, v12
	v_cmp_lt_f32_e64 s[50:51], |v12|, s30
	s_nop 1
	v_cndmask_b32_e64 v12, v12, v21, s[50:51]
	v_cndmask_b32_e32 v21, 0, v190, vcc
	v_cmp_gt_f32_e32 vcc, s28, v13
	v_sub_f32_e32 v12, v12, v21
	s_nop 0
	v_cndmask_b32_e64 v21, 0, 32, vcc
	v_ldexp_f32 v13, v13, v21
	v_log_f32_e32 v13, v13
	s_nop 0
	v_mul_f32_e32 v21, 0x3f317217, v13
	v_fma_f32 v21, v13, s29, -v21
	v_fmac_f32_e32 v21, 0x3377d1cf, v13
	v_fmac_f32_e32 v21, 0x3f317217, v13
	v_cmp_lt_f32_e64 s[50:51], |v13|, s30
	s_nop 1
	v_cndmask_b32_e64 v13, v13, v21, s[50:51]
	v_cndmask_b32_e32 v21, 0, v190, vcc
	v_sub_f32_e32 v13, v13, v21
	v_mul_f32_e32 v21, 0xbfb8aa3b, v42
	v_exp_f32_e32 v21, v21
	s_nop 0
	v_add_f32_e32 v21, 1.0, v21
	v_rcp_f32_e32 v46, v21
	v_mul_f32_e32 v21, 0xbfb8aa3b, v43
	v_exp_f32_e32 v21, v21
	v_pk_add_f32 v[42:43], v[14:15], 1.0 op_sel_hi:[1,0] neg_lo:[1,0] neg_hi:[1,0]
	v_add_f32_e32 v21, 1.0, v21
	v_fma_f32 v14, v46, v42, v14
	v_cmp_gt_f32_e32 vcc, s28, v14
	v_rcp_f32_e32 v47, v21
	s_nop 0
	v_cndmask_b32_e64 v21, 0, 32, vcc
	v_ldexp_f32 v14, v14, v21
	v_log_f32_e32 v14, v14
	v_fmac_f32_e32 v15, v47, v43
	v_mul_f32_e32 v21, 0x3f317217, v14
	v_fma_f32 v21, v14, s29, -v21
	v_fmac_f32_e32 v21, 0x3377d1cf, v14
	v_fmac_f32_e32 v21, 0x3f317217, v14
	v_cmp_lt_f32_e64 s[50:51], |v14|, s30
	s_nop 1
	v_cndmask_b32_e64 v14, v14, v21, s[50:51]
	v_cndmask_b32_e32 v21, 0, v190, vcc
	v_cmp_gt_f32_e32 vcc, s28, v15
	v_sub_f32_e32 v14, v14, v21
	s_nop 0
	v_cndmask_b32_e64 v21, 0, 32, vcc
	v_ldexp_f32 v15, v15, v21
	v_log_f32_e32 v15, v15
	s_nop 0
	v_mul_f32_e32 v21, 0x3f317217, v15
	v_fma_f32 v21, v15, s29, -v21
	v_fmac_f32_e32 v21, 0x3377d1cf, v15
	v_fmac_f32_e32 v21, 0x3f317217, v15
	v_cmp_lt_f32_e64 s[50:51], |v15|, s30
	s_nop 1
	v_cndmask_b32_e64 v15, v15, v21, s[50:51]
	v_cndmask_b32_e32 v21, 0, v190, vcc
	v_sub_f32_e32 v15, v15, v21
	ds_write_b128 v66, v[16:19]
	ds_write_b128 v66, v[12:15] offset:16
	v_lshlrev_b32_e32 v16, 16, v8
	v_mul_f32_e32 v16, 0xbfb8aa3b, v16
	v_exp_f32_e32 v16, v16
	v_and_b32_e32 v17, 0xffff0000, v8
	v_lshlrev_b32_e32 v18, 16, v9
	v_and_b32_e32 v19, 0xffff0000, v9
	v_lshlrev_b32_e32 v21, 16, v10
	ds_read_b128 v[12:15], v20
	ds_read_b128 v[8:11], v20 offset:16
	v_add_f32_e32 v16, 1.0, v16
	v_rcp_f32_e32 v50, v16
	v_mul_f32_e32 v16, 0xbfb8aa3b, v17
	v_exp_f32_e32 v16, v16
	s_waitcnt lgkmcnt(1)
; #define LAS __attribute__((address_space(3)))
; __device__ __forceinline__ float bflo(unsigned u) { return __uint_as_float(u << 16); }
; __device__ __forceinline__ float bfhi(unsigned u) { return __uint_as_float(u & 0xffff0000u); }
; __device__ __forceinline__ float sigm(float x) { return frcp(1.f + fexp(-x)); }
; __device__ __forceinline__ void hgrn_stepA(const Args& a, int l, LAS unsigned char* lds, int tid, int hh, const HIn& in, float (&kf)[16]) {
;     ...
;     for (int ii = 0; ii < 2; ++ii) {
;         const int cid = tid + 512 * ii, t = cid >> 4, d0 = (cid & 15) * 8;
;         const u32x4 u = in.f[ii];
;         float fl[8] = {bflo(u.x), bfhi(u.x), bflo(u.y), bfhi(u.y), bflo(u.z), bfhi(u.z), bflo(u.w), bfhi(u.w)};
;         float lf[8];
;         const LAS float* LB = (const LAS float*)(lds + 106496) + hh * 128 + d0; const f32x4 lb0 = *(const LAS f32x4*)LB, lb1 = *(const LAS f32x4*)(LB + 4);
;         const float lbv[8] = {lb0.x, lb0.y, lb0.z, lb0.w, lb1.x, lb1.y, lb1.z, lb1.w};
; #pragma unroll
;         for (int i = 0; i < 8; ++i) { const float lb = lbv[i]; const float sg = sigm(fl[i]);
;             const float f = lb + (1.f - lb) * sg; lf[i] = __logf(f); kf[ii * 8 + i] = (1.f - lb) * (1.f - sg); }
;         *(LAS f32x4*)(LF + t * 128 + d0) = (f32x4){lf[0], lf[1], lf[2], lf[3]}; *(LAS f32x4*)(LF + t * 128 + d0 + 4) = (f32x4){lf[4], lf[5], lf[6], lf[7]};
;     }
; }
; __device__ __forceinline__ void hgrn_cumsum_scan(LAS unsigned char* lds, int tid) {
;     LAS float* LF = (LAS float*)lds;
;     LAS float* PT = (LAS float*)(lds + 32768);
;     BAR_LDS();
;     const int d = tid & 127, pt = tid >> 7;
;     float v[16];
; #pragma unroll
;     for (int t = 0; t < 16; ++t) v[t] = LF[(pt * 16 + t) * 128 + d];
; #pragma unroll
;     for (int t = 1; t < 16; ++t) v[t] += v[t - 1];
;     PT[pt * 128 + d] = v[15];
;     BAR_LDS();
;     { float off = 0.f;
; #pragma unroll
;       for (int p = 0; p < 3; ++p) off += (p < pt) ? PT[p * 128 + d] : 0.f;
; #pragma unroll
;       for (int t = 0; t < 16; ++t) LF[(pt * 16 + t) * 128 + d] = v[t] + off; }
; __device__ __forceinline__ void hgrn_stage1_unit(const Args& a, int l, LAS unsigned char* lds, int tid, int u, const HIn& in, HIn& nxt, int unext) {
;     ...
;     hgrn_load<false>(a, tid, unext, nxt);
	v_pk_add_f32 v[44:45], v[12:13], 1.0 op_sel_hi:[1,0] neg_lo:[1,0] neg_hi:[1,0]
	v_pk_add_f32 v[48:49], v[14:15], 1.0 op_sel_hi:[1,0] neg_lo:[1,0] neg_hi:[1,0]
	v_fma_f32 v12, v50, v44, v12
	v_add_f32_e32 v16, 1.0, v16
	v_cmp_gt_f32_e32 vcc, s28, v12
	v_rcp_f32_e32 v51, v16
	s_waitcnt lgkmcnt(0)
	v_pk_add_f32 v[52:53], v[8:9], 1.0 op_sel_hi:[1,0] neg_lo:[1,0] neg_hi:[1,0]
	v_cndmask_b32_e64 v16, 0, 32, vcc
	v_ldexp_f32 v12, v12, v16
	v_log_f32_e32 v12, v12
	v_fma_f32 v13, v51, v45, v13
	v_pk_add_f32 v[54:55], v[10:11], 1.0 op_sel_hi:[1,0] neg_lo:[1,0] neg_hi:[1,0]
	v_mul_f32_e32 v16, 0x3f317217, v12
	v_fma_f32 v16, v12, s29, -v16
	v_fmac_f32_e32 v16, 0x3377d1cf, v12
	v_fmac_f32_e32 v16, 0x3f317217, v12
	v_cmp_lt_f32_e64 s[50:51], |v12|, s30
	s_nop 1
	v_cndmask_b32_e64 v12, v12, v16, s[50:51]
	v_cndmask_b32_e32 v16, 0, v190, vcc
	v_cmp_gt_f32_e32 vcc, s28, v13
	v_sub_f32_e32 v12, v12, v16
	s_nop 0
	v_cndmask_b32_e64 v16, 0, 32, vcc
	v_ldexp_f32 v13, v13, v16
	v_log_f32_e32 v13, v13
	s_nop 0
	v_mul_f32_e32 v16, 0x3f317217, v13
	v_fma_f32 v16, v13, s29, -v16
	v_fmac_f32_e32 v16, 0x3377d1cf, v13
	v_fmac_f32_e32 v16, 0x3f317217, v13
	v_cmp_lt_f32_e64 s[50:51], |v13|, s30
	s_nop 1
	v_cndmask_b32_e64 v13, v13, v16, s[50:51]
	v_cndmask_b32_e32 v16, 0, v190, vcc
	v_sub_f32_e32 v13, v13, v16
	v_mul_f32_e32 v16, 0xbfb8aa3b, v18
	v_exp_f32_e32 v16, v16
	s_nop 0
	v_add_f32_e32 v16, 1.0, v16
	v_rcp_f32_e32 v56, v16
	v_mul_f32_e32 v16, 0xbfb8aa3b, v19
	v_exp_f32_e32 v16, v16
	v_fma_f32 v14, v56, v48, v14
	v_cmp_gt_f32_e32 vcc, s28, v14
	v_add_f32_e32 v16, 1.0, v16
	v_rcp_f32_e32 v57, v16
	v_cndmask_b32_e64 v16, 0, 32, vcc
	v_ldexp_f32 v14, v14, v16
	v_log_f32_e32 v14, v14
	v_fmac_f32_e32 v15, v57, v49
	v_mul_f32_e32 v16, 0x3f317217, v14
	v_fma_f32 v16, v14, s29, -v16
	v_fmac_f32_e32 v16, 0x3377d1cf, v14
	v_fmac_f32_e32 v16, 0x3f317217, v14
	v_cmp_lt_f32_e64 s[50:51], |v14|, s30
	s_nop 1
	v_cndmask_b32_e64 v14, v14, v16, s[50:51]
	v_cndmask_b32_e32 v16, 0, v190, vcc
	v_cmp_gt_f32_e32 vcc, s28, v15
	v_sub_f32_e32 v14, v14, v16
	s_nop 0
	v_cndmask_b32_e64 v16, 0, 32, vcc
	v_ldexp_f32 v15, v15, v16
	v_log_f32_e32 v15, v15
	s_nop 0
	v_mul_f32_e32 v16, 0x3f317217, v15
	v_fma_f32 v16, v15, s29, -v16
	v_fmac_f32_e32 v16, 0x3377d1cf, v15
	v_fmac_f32_e32 v16, 0x3f317217, v15
	v_cmp_lt_f32_e64 s[50:51], |v15|, s30
	s_nop 1
	v_cndmask_b32_e64 v15, v15, v16, s[50:51]
	v_cndmask_b32_e32 v16, 0, v190, vcc
	v_sub_f32_e32 v15, v15, v16
	v_mul_f32_e32 v16, 0xbfb8aa3b, v21
	v_exp_f32_e32 v16, v16
	s_nop 0
	v_add_f32_e32 v16, 1.0, v16
	v_rcp_f32_e32 v58, v16
	v_mul_f32_e32 v16, 0xbfb8aa3b, v22
	v_exp_f32_e32 v16, v16
	v_fma_f32 v8, v58, v52, v8
	v_cmp_gt_f32_e32 vcc, s28, v8
	v_add_f32_e32 v16, 1.0, v16
	v_rcp_f32_e32 v59, v16
	v_cndmask_b32_e64 v16, 0, 32, vcc
	v_ldexp_f32 v8, v8, v16
	v_log_f32_e32 v8, v8
	v_fma_f32 v9, v59, v53, v9
	v_mul_f32_e32 v16, 0x3f317217, v8
	v_fma_f32 v16, v8, s29, -v16
	v_fmac_f32_e32 v16, 0x3377d1cf, v8
	v_fmac_f32_e32 v16, 0x3f317217, v8
	v_cmp_lt_f32_e64 s[50:51], |v8|, s30
	s_nop 1
	v_cndmask_b32_e64 v8, v8, v16, s[50:51]
	v_cndmask_b32_e32 v16, 0, v190, vcc
	v_cmp_gt_f32_e32 vcc, s28, v9
	v_sub_f32_e32 v8, v8, v16
	s_nop 0
	v_cndmask_b32_e64 v16, 0, 32, vcc
	v_ldexp_f32 v9, v9, v16
	v_log_f32_e32 v9, v9
	s_nop 0
	v_mul_f32_e32 v16, 0x3f317217, v9
	v_fma_f32 v16, v9, s29, -v16
	v_fmac_f32_e32 v16, 0x3377d1cf, v9
	v_fmac_f32_e32 v16, 0x3f317217, v9
	v_cmp_lt_f32_e64 s[50:51], |v9|, s30
	s_nop 1
	v_cndmask_b32_e64 v9, v9, v16, s[50:51]
	v_cndmask_b32_e32 v16, 0, v190, vcc
	v_sub_f32_e32 v9, v9, v16
	v_mul_f32_e32 v16, 0xbfb8aa3b, v23
	v_exp_f32_e32 v16, v16
	s_nop 0
	v_add_f32_e32 v16, 1.0, v16
	v_rcp_f32_e32 v62, v16
	v_mul_f32_e32 v16, 0xbfb8aa3b, v37
	v_exp_f32_e32 v16, v16
	v_fma_f32 v10, v62, v54, v10
	v_cmp_gt_f32_e32 vcc, s28, v10
	v_add_f32_e32 v16, 1.0, v16
	v_rcp_f32_e32 v63, v16
	v_cndmask_b32_e64 v16, 0, 32, vcc
	v_ldexp_f32 v10, v10, v16
	v_log_f32_e32 v10, v10
	v_fmac_f32_e32 v11, v63, v55
	v_mul_f32_e32 v16, 0x3f317217, v10
	v_fma_f32 v16, v10, s29, -v16
	v_fmac_f32_e32 v16, 0x3377d1cf, v10
	v_fmac_f32_e32 v16, 0x3f317217, v10
	v_cmp_lt_f32_e64 s[50:51], |v10|, s30
	s_nop 1
	v_cndmask_b32_e64 v10, v10, v16, s[50:51]
	v_cndmask_b32_e32 v16, 0, v190, vcc
	v_cmp_gt_f32_e32 vcc, s28, v11
	v_sub_f32_e32 v10, v10, v16
	s_nop 0
	v_cndmask_b32_e64 v16, 0, 32, vcc
	v_ldexp_f32 v11, v11, v16
	v_log_f32_e32 v11, v11
	s_nop 0
	v_mul_f32_e32 v16, 0x3f317217, v11
	v_fma_f32 v16, v11, s29, -v16
	v_fmac_f32_e32 v16, 0x3377d1cf, v11
	v_fmac_f32_e32 v16, 0x3f317217, v11
	v_cmp_lt_f32_e64 s[50:51], |v11|, s30
	s_nop 1
	v_cndmask_b32_e64 v11, v11, v16, s[50:51]
	v_cndmask_b32_e32 v16, 0, v190, vcc
	v_sub_f32_e32 v11, v11, v16
	ds_write_b128 v66, v[12:15] offset:16384
	ds_write_b128 v66, v[8:11] offset:16400
	v_lshl_add_u64 v[8:9], s[10:11], 0, v[32:33]
	v_lshlrev_b64 v[8:9], 13, v[8:9]
	v_lshl_add_u64 v[8:9], s[84:85], 0, v[8:9]
	v_lshl_add_u64 v[8:9], v[8:9], 0, s[6:7]
	v_lshl_add_u64 v[8:9], v[8:9], 0, v[144:145]
	v_add_co_u32_e32 v8, vcc, s26, v8
	s_nop 1
	v_addc_co_u32_e32 v9, vcc, 0, v9, vcc
	global_load_dwordx4 v[12:15], v[8:9], off offset:2048
	global_load_dwordx4 v[16:19], v[8:9], off offset:3072
	v_lshl_add_u64 v[8:9], s[10:11], 0, v[34:35]
	v_lshlrev_b64 v[8:9], 13, v[8:9]
	v_lshl_add_u64 v[8:9], s[84:85], 0, v[8:9]
	v_lshl_add_u64 v[8:9], v[8:9], 0, s[6:7]
	v_lshl_add_u64 v[8:9], v[8:9], 0, v[144:145]
	v_add_co_u32_e32 v20, vcc, s26, v8
	s_nop 1
	v_addc_co_u32_e32 v21, vcc, 0, v9, vcc
	global_load_dwordx4 v[8:11], v[20:21], off offset:2048
	s_nop 0
	global_load_dwordx4 v[20:23], v[20:21], off offset:3072
	s_waitcnt lgkmcnt(0)
	s_barrier
	ds_read2st64_b32 v[60:61], v68 offset1:2
	ds_read2st64_b32 v[80:81], v68 offset0:4 offset1:6
	ds_read2st64_b32 v[82:83], v68 offset0:8 offset1:10
	ds_read2st64_b32 v[84:85], v68 offset0:12 offset1:14
	ds_read2st64_b32 v[94:95], v68 offset0:16 offset1:18
	ds_read2st64_b32 v[98:99], v68 offset0:20 offset1:22
	ds_read2st64_b32 v[102:103], v68 offset0:24 offset1:26
	ds_read2st64_b32 v[104:105], v68 offset0:28 offset1:30
	s_waitcnt lgkmcnt(7)
	v_add_f32_e32 v92, v60, v61
	s_waitcnt lgkmcnt(6)
	v_add_f32_e32 v90, v80, v92
	v_add_f32_e32 v91, v81, v90
	s_waitcnt lgkmcnt(5)
	v_add_f32_e32 v88, v82, v91
	v_add_f32_e32 v89, v83, v88
	s_waitcnt lgkmcnt(4)
	v_add_f32_e32 v86, v84, v89
	v_add_f32_e32 v87, v85, v86
	s_waitcnt lgkmcnt(3)
	v_add_f32_e32 v84, v94, v87
	v_add_f32_e32 v85, v95, v84
	s_waitcnt lgkmcnt(2)
	v_add_f32_e32 v82, v98, v85
	v_add_f32_e32 v83, v99, v82
	s_waitcnt lgkmcnt(1)
	v_add_f32_e32 v80, v102, v83
	v_add_f32_e32 v81, v103, v80
	s_waitcnt lgkmcnt(0)
	v_add_f32_e32 v37, v104, v81
	v_add_f32_e32 v61, v105, v37
	ds_write_b32 v101, v61 offset:32768
	s_waitcnt lgkmcnt(0)
	s_barrier
	v_mov_b32_e32 v94, 0
	s_and_saveexec_b64 s[14:15], s[44:45]
	s_cbranch_execnz .LBB0_446
	s_or_b64 exec, exec, s[14:15]
	v_mov_b32_e32 v95, 0
	s_and_saveexec_b64 s[14:15], s[46:47]
	s_cbranch_execnz .LBB0_447

; #define SEAM(k) do { if (IN(k) && IN((k) + 1)) { if (a.pad == 0x5eed) cg::this_grid().sync(); xcd_barrier(xbar); } } while (0)
; __global__ void __launch_bounds__(512) hymba_fwd(Args a) {
;     ...
;         SEAM(base + 2);
.LBB0_449:
	v_readlane_b32 s4, v244, 60
	v_readlane_b32 s8, v246, 0
	s_add_i32 s4, s4, 3
	v_readlane_b32 s9, v246, 1
	s_cmp_ge_i32 s4, s9
	s_cbranch_scc1 .LBB0_511
	s_cmp_eq_u32 s3, 0x100
	s_cbranch_scc1 .Lbbsb1
	s_and_b64 vcc, exec, s[96:97]
	s_cbranch_vccnz .LBB0_462
	s_barrier
	s_mov_b64 s[14:15], exec
	v_readlane_b32 s8, v244, 4
	v_readlane_b32 s9, v244, 5
	s_and_b64 s[8:9], s[14:15], s[8:9]
	s_mov_b64 exec, s[8:9]
	s_cbranch_execz .LBB0_461
	v_readlane_b32 s8, v246, 2
	v_readlane_b32 s9, v246, 3
	buffer_wbl2 sc1
	s_waitcnt vmcnt(0)
	s_load_dwordx2 s[16:17], s[8:9], 0x58
	s_mov_b64 s[18:19], exec
	v_mbcnt_lo_u32_b32 v1, s18, 0
	v_mbcnt_hi_u32_b32 v1, s19, v1
	v_cmp_eq_u32_e32 vcc, 0, v1
	s_waitcnt lgkmcnt(0)
	global_load_dword v0, v145, s[16:17] offset:40
	s_and_saveexec_b64 s[40:41], vcc
	s_cbranch_execz .LBB0_454
	s_bcnt1_i32_b64 s5, s[18:19]
	v_mov_b32_e32 v2, s5
	global_atomic_add v2, v145, v2, s[16:17] offset:32 sc0

; #define SEAM(k) do { if (IN(k) && IN((k) + 1)) { if (a.pad == 0x5eed) cg::this_grid().sync(); xcd_barrier(xbar); } } while (0)
; __global__ void __launch_bounds__(512) hymba_fwd(Args a) {
;     ...
;         SEAM(base + 3);
.Lx2_end:
	v_readlane_b32 s4, v244, 60
	v_readlane_b32 s8, v246, 0
	s_add_i32 s4, s4, 4
	v_readlane_b32 s9, v246, 1
	s_cmp_lt_i32 s4, s9
	s_barrier
	s_cbranch_scc0 .LBB0_634
	s_cmp_eq_u32 s3, 0x100
	s_cbranch_scc1 .Lbbsb2
	s_and_b64 vcc, exec, s[96:97]
	s_cbranch_vccnz .LBB0_540
	s_barrier
	s_mov_b64 s[14:15], exec
	v_readlane_b32 s8, v244, 4
	v_readlane_b32 s9, v244, 5
	s_and_b64 s[8:9], s[14:15], s[8:9]
	s_mov_b64 exec, s[8:9]
	s_cbranch_execz .LBB0_539
	v_readlane_b32 s8, v246, 2
	v_readlane_b32 s9, v246, 3
	buffer_wbl2 sc1
	s_waitcnt vmcnt(0)
	s_load_dwordx2 s[16:17], s[8:9], 0x58
	s_mov_b64 s[18:19], exec
	v_mbcnt_lo_u32_b32 v1, s18, 0
	v_mbcnt_hi_u32_b32 v1, s19, v1
	v_cmp_eq_u32_e32 vcc, 0, v1
	s_waitcnt lgkmcnt(0)
	global_load_dword v0, v145, s[16:17] offset:40
	s_and_saveexec_b64 s[40:41], vcc
	s_cbranch_execz .LBB0_532
	s_bcnt1_i32_b64 s5, s[18:19]
	v_mov_b32_e32 v2, s5
	global_atomic_add v2, v145, v2, s[16:17] offset:32 sc0

; #define LAS __attribute__((address_space(3)))
; __device__ __forceinline__ int otid() { int t = threadIdx.x; asm volatile("" : "+v"(t)); return t; }
; template <bool NEEDQ>
; __device__ __forceinline__ void hgrn_load(const Args& a, int tid, int u, HIn& r) {
;     const int bh = u >> 5, c = u & 31, b = bh >> 2, hh = bh & 3; const size_t row0 = (size_t)b * SEQ + c * 64;
; #pragma unroll
;     for (int ii = 0; ii < 2; ++ii) { const int cid = tid + 512 * ii, t = cid >> 4, d0 = (cid & 15) * 8;
;         const bf16_t* p = (const bf16_t*)(a.ws + WS_PROJ) + (row0 + t) * NCOL + hh * 128 + d0;
;         r.f[ii] = *(const u32x4*)(p + CFH); r.v[ii] = *(const u32x4*)(p + CIH); if (NEEDQ) r.q[ii] = *(const u32x4*)(p + CQH); }
; }
; __global__ void __launch_bounds__(512) hymba_fwd(Args a) {
;     ...
;             { const int tid = otid();
;               if (tid < 512) ((LAS float*)(lds + 106496))[tid] = ((const float*)(a.ws + WS_LB))[l * 512 + tid];
;               if (tid < 128) ((LAS float*)(lds + 106496 + 2048))[tid] = a.hon[l * 128 + tid];
;               __syncthreads();
;               HIn cur; int u = bx; hgrn_load<true>(a, tid, u < 1024 ? u : 0, cur);
;                 for (; u < 1024; u += G) { HIn nxt; hgrn_stage3_unit(a, l, lds, tid, u, cur, nxt, (u + G < 1024) ? u + G : u); cur = nxt; } }
.LBB0_641:
	s_or_b64 exec, exec, s[14:15]
	v_readlane_b32 s4, v245, 56
	v_readlane_b32 s5, v245, 57
	s_andn2_b64 vcc, exec, s[4:5]
	s_waitcnt lgkmcnt(0)
	s_barrier
	s_cbranch_vccnz .LBB0_680
	v_add_u32_e32 v0, 0x200, v121
	v_ashrrev_i32_e32 v118, 4, v0
	v_readlane_b32 s4, v245, 58
	v_ashrrev_i32_e32 v119, 31, v118
	v_readlane_b32 s5, v245, 59
	v_lshlrev_b32_e32 v9, 3, v121
	v_ashrrev_i32_e32 v116, 4, v121
	v_lshl_add_u64 v[0:1], s[4:5], 0, v[118:119]
	v_readlane_b32 s8, v245, 60
	v_and_b32_e32 v8, 0x78, v9
	v_ashrrev_i32_e32 v117, 31, v116
	v_lshlrev_b64 v[0:1], 13, v[0:1]
	v_readlane_b32 s9, v245, 61
	v_lshlrev_b32_e32 v144, 1, v8
	v_lshl_add_u64 v[6:7], s[4:5], 0, v[116:117]
	v_lshl_add_u64 v[0:1], s[8:9], 0, v[0:1]
	v_lshl_add_u64 v[0:1], v[0:1], 0, v[144:145]
	v_lshlrev_b64 v[6:7], 13, v[6:7]
	v_add_co_u32_e32 v4, vcc, s26, v0
	v_lshl_add_u64 v[6:7], s[8:9], 0, v[6:7]
	s_nop 0
	v_addc_co_u32_e32 v5, vcc, 0, v1, vcc
	v_lshl_add_u64 v[6:7], v[6:7], 0, v[144:145]
	global_load_dwordx4 v[28:31], v[0:1], off offset:1024
	s_nop 0
	global_load_dwordx4 v[0:3], v[4:5], off offset:2048
	global_load_dwordx4 v[24:27], v[4:5], off offset:3072
	global_load_dwordx4 v[100:103], v[6:7], off offset:1024
	v_add_co_u32_e32 v4, vcc, s26, v6
	v_bfe_u32 v11, v121, 4, 2
	s_nop 0
	v_addc_co_u32_e32 v5, vcc, 0, v7, vcc
	global_load_dwordx4 v[72:75], v[4:5], off offset:3072
	s_nop 0
	global_load_dwordx4 v[4:7], v[4:5], off offset:2048
	v_lshlrev_b32_e32 v122, 2, v11
	s_add_i32 s4, 0, 0x1a000
	v_lshlrev_b32_e32 v10, 2, v8
	v_and_b32_e32 v120, 15, v121
	v_or_b32_e32 v32, 2, v122
	v_add_u32_e32 v170, s4, v10
	v_add_u32_e32 v171, 0, v10
	v_lshlrev_b32_e32 v10, 5, v121
	v_and_b32_e32 v12, 0x7f, v121
	v_readlane_b32 s4, v244, 53
	v_cmp_gt_u32_e64 s[52:53], v32, v120
	v_or_b32_e32 v32, 3, v122
	v_and_b32_e32 v10, 0xfffffe00, v10
	v_ashrrev_i32_e32 v13, 7, v121
	v_lshl_add_u32 v174, v12, 2, 0
	v_readlane_b32 s5, v244, 54
	v_lshlrev_b32_e32 v17, 4, v11
	v_mov_b32_e32 v21, s4
	v_cmp_gt_u32_e64 s[54:55], v32, v120
	v_bfe_u32 v32, v121, 2, 2
	v_add_u32_e32 v172, v171, v10
	v_lshlrev_b32_e32 v10, 3, v11
	v_lshl_add_u32 v175, v13, 13, v174
	v_cmp_lt_i32_e64 s[42:43], 0, v13
	v_cmp_lt_i32_e64 s[44:45], 1, v13
	v_cmp_lt_i32_e64 s[46:47], 2, v13
	v_add_u32_e32 v177, s4, v144
	v_add_u32_e32 v12, s5, v144
	v_lshlrev_b32_e32 v13, 9, v116
	v_mul_lo_u32 v14, v116, s27
	v_lshlrev_b32_e32 v15, 9, v118
	v_mul_lo_u32 v16, v118, s27
	v_add_u32_e32 v18, s4, v17
	v_mul_u32_u24_e32 v19, 0x110, v120
	v_or_b32_e32 v20, 64, v17
	v_mad_u32_u24 v21, v120, s31, v21
	v_or_b32_e32 v22, 0x80, v17
	v_or_b32_e32 v23, 0xc0, v17
	v_and_b32_e32 v182, 24, v9
	v_or_b32_e32 v9, v122, v32
	v_mov_b32_e32 v32, s5
	v_readlane_b32 s4, v244, 55
	v_lshlrev_b32_e32 v173, 7, v120
	v_sub_u32_e32 v176, v171, v144
	v_mul_lo_u32 v180, v116, s31
	v_mul_lo_u32 v181, v118, s31
	v_cmp_gt_u32_e64 s[48:49], v122, v120
	v_cmp_ge_u32_e64 s[50:51], v122, v120
	v_mad_u32_u24 v183, v9, s27, v32
	v_add_u32_e32 v195, 0, v17
	v_cmp_eq_u32_e64 s[56:57], 0, v11
	v_lshl_add_u32 v196, v120, 2, s4
	v_lshlrev_b32_e32 v144, 1, v10
	v_lshlrev_b32_e32 v124, 1, v8
	v_add_u32_e32 v197, v171, v13
	v_add_u32_e32 v198, v12, v14
	v_add_u32_e32 v199, v171, v15
	v_add_u32_e32 v200, v12, v16
	v_add_u32_e32 v201, v18, v19
	v_add_u32_e32 v202, v21, v20
	v_add_u32_e32 v203, v21, v22
	v_add_u32_e32 v204, v21, v23
	s_mov_b32 s8, s2
	s_mov_b32 s98, s3
	s_movk_i32 s99, 0x400
	s_cmp_eq_u32 s3, 0x100
	s_cbranch_scc0 .Lrm_s3
	s_and_b32 s8, s2, 7
	s_lshl_b32 s8, s8, 7
	s_add_i32 s99, s8, 0x80
	s_lshr_b32 s98, s2, 3
	s_or_b32 s8, s8, s98
	s_mov_b32 s98, 32

; #define LAS __attribute__((address_space(3)))
; __device__ __forceinline__ float bflo(unsigned u) { return __uint_as_float(u << 16); }
; __device__ __forceinline__ float bfhi(unsigned u) { return __uint_as_float(u & 0xffff0000u); }
; __device__ __forceinline__ float sigm(float x) { return frcp(1.f + fexp(-x)); }
; __device__ __forceinline__ void hgrn_stepA(const Args& a, int l, LAS unsigned char* lds, int tid, int hh, const HIn& in, float (&kf)[16]) {
;     LAS float* LF = (LAS float*)lds;
;     LAS float* PT = (LAS float*)(lds + 32768);
; #pragma unroll
;     for (int ii = 0; ii < 2; ++ii) {
;         const int cid = tid + 512 * ii, t = cid >> 4, d0 = (cid & 15) * 8;
;         const u32x4 u = in.f[ii];
;         float fl[8] = {bflo(u.x), bfhi(u.x), bflo(u.y), bfhi(u.y), bflo(u.z), bfhi(u.z), bflo(u.w), bfhi(u.w)};
;         float lf[8];
;         const LAS float* LB = (const LAS float*)(lds + 106496) + hh * 128 + d0; const f32x4 lb0 = *(const LAS f32x4*)LB, lb1 = *(const LAS f32x4*)(LB + 4);
;         const float lbv[8] = {lb0.x, lb0.y, lb0.z, lb0.w, lb1.x, lb1.y, lb1.z, lb1.w};
; #pragma unroll
;         for (int i = 0; i < 8; ++i) { const float lb = lbv[i]; const float sg = sigm(fl[i]);
;             const float f = lb + (1.f - lb) * sg; lf[i] = __logf(f); kf[ii * 8 + i] = (1.f - lb) * (1.f - sg); }
;         *(LAS f32x4*)(LF + t * 128 + d0) = (f32x4){lf[0], lf[1], lf[2], lf[3]}; *(LAS f32x4*)(LF + t * 128 + d0 + 4) = (f32x4){lf[4], lf[5], lf[6], lf[7]};
; __device__ __forceinline__ void hgrn_stage3_unit(const Args& a, int l, LAS unsigned char* lds, int tid, int u, const HIn& in, HIn& nxt, int unext) {
;     const int lane = tid & 63, w = __builtin_amdgcn_readfirstlane(tid >> 6), fr = lane & 15, fq = lane >> 4;
;     const int bh = u >> 5, c = u & 31, b = bh >> 2, hh = bh & 3; const size_t row0 = (size_t)b * SEQ + c * 64;
;     const int tt = w & 3, vh = w >> 2;
;     bf16_t* proj = (bf16_t*)(a.ws + WS_PROJ);
;     LAS float* LF = (LAS float*)lds;
;     LAS unsigned char* QM = lds + 34816;
;     LAS unsigned char* Q0 = QM + 17408;
;     LAS unsigned char* KM = Q0 + 17408;
;     LAS unsigned char* VN = KM + 17408;
;     LAS float* SSQ = (LAS float*)(VN + 18432);
;     float kf[16];
;     hgrn_stepA(a, l, lds, tid, hh, in, kf);
.LBB0_644:
	s_mov_b32 s4, s8
	s_add_i32 s8, s8, s98
	s_waitcnt vmcnt(0)
	v_lshlrev_b32_e32 v13, 16, v4
	s_cmp_ge_i32 s8, s99
	v_mul_f32_e32 v13, 0xbfb8aa3b, v13
	s_cselect_b64 s[70:71], -1, 0
	s_cmp_lt_i32 s8, s99
	v_exp_f32_e32 v13, v13
	s_cselect_b32 s5, s8, s4
	s_ashr_i32 s60, s4, 5
	s_and_b32 s9, s60, 3
	v_lshl_add_u32 v12, s9, 9, v170
	v_and_b32_e32 v14, 0xffff0000, v4
	v_lshlrev_b32_e32 v15, 16, v5
	v_and_b32_e32 v16, 0xffff0000, v5
	v_lshlrev_b32_e32 v17, 16, v6
	v_and_b32_e32 v18, 0xffff0000, v6
	v_lshlrev_b32_e32 v19, 16, v7
	v_and_b32_e32 v20, 0xffff0000, v7
	ds_read_b128 v[8:11], v12
	ds_read_b128 v[4:7], v12 offset:16
	v_add_f32_e32 v13, 1.0, v13
	v_rcp_f32_e32 v104, v13
	v_mul_f32_e32 v13, 0xbfb8aa3b, v14
	v_exp_f32_e32 v13, v13
	s_waitcnt lgkmcnt(1)
	v_pk_add_f32 v[106:107], v[8:9], 1.0 op_sel_hi:[1,0] neg_lo:[1,0] neg_hi:[1,0]
	v_pk_add_f32 v[110:111], v[10:11], 1.0 op_sel_hi:[1,0] neg_lo:[1,0] neg_hi:[1,0]
	v_fma_f32 v8, v104, v106, v8
	v_add_f32_e32 v13, 1.0, v13
	v_cmp_gt_f32_e32 vcc, s28, v8
	v_rcp_f32_e32 v105, v13
	s_waitcnt lgkmcnt(0)
	v_pk_add_f32 v[114:115], v[4:5], 1.0 op_sel_hi:[1,0] neg_lo:[1,0] neg_hi:[1,0]
	v_cndmask_b32_e64 v13, 0, 32, vcc
	v_ldexp_f32 v8, v8, v13
	v_log_f32_e32 v8, v8
	v_fma_f32 v9, v105, v107, v9
	v_pk_add_f32 v[138:139], v[6:7], 1.0 op_sel_hi:[1,0] neg_lo:[1,0] neg_hi:[1,0]
	v_and_b32_e32 v14, 0xffff0000, v2
	v_mul_f32_e32 v13, 0x3f317217, v8
	v_fma_f32 v13, v8, s29, -v13
	v_fmac_f32_e32 v13, 0x3377d1cf, v8
	v_fmac_f32_e32 v13, 0x3f317217, v8
	v_cmp_lt_f32_e64 s[58:59], |v8|, s30
	v_readfirstlane_b32 s10, v121
	s_and_b32 s14, s4, 31
	v_cndmask_b32_e64 v8, v8, v13, s[58:59]
	v_cndmask_b32_e32 v13, 0, v190, vcc
	v_cmp_gt_f32_e32 vcc, s28, v9
	v_sub_f32_e32 v8, v8, v13
	s_ashr_i32 s40, s4, 7
	v_cndmask_b32_e64 v13, 0, 32, vcc
	v_ldexp_f32 v9, v9, v13
	v_log_f32_e32 v9, v9
	s_bfe_u32 s11, s10, 0x20006
	s_ashr_i32 s61, s60, 31
	s_ashr_i32 s41, s40, 31
	v_mul_f32_e32 v13, 0x3f317217, v9
	v_fma_f32 v13, v9, s29, -v13
	v_fmac_f32_e32 v13, 0x3377d1cf, v9
	v_fmac_f32_e32 v13, 0x3f317217, v9
	v_cmp_lt_f32_e64 s[58:59], |v9|, s30
	s_lshl_b32 s6, s14, 6
	s_ashr_i32 s36, s10, 8
	v_cndmask_b32_e64 v9, v9, v13, s[58:59]
	v_cndmask_b32_e32 v13, 0, v190, vcc
	v_sub_f32_e32 v9, v9, v13
	v_mul_f32_e32 v13, 0xbfb8aa3b, v15
	v_exp_f32_e32 v13, v13
	v_lshlrev_b32_e32 v15, 16, v3
	s_lshl_b32 s4, s11, 4
	s_lshl_b64 s[16:17], s[60:61], 20
	v_add_f32_e32 v13, 1.0, v13
	v_rcp_f32_e32 v108, v13
	v_mul_f32_e32 v13, 0xbfb8aa3b, v16
	v_exp_f32_e32 v13, v13
	v_and_b32_e32 v16, 0xffff0000, v3
	v_fma_f32 v10, v108, v110, v10
	v_cmp_gt_f32_e32 vcc, s28, v10
	v_add_f32_e32 v13, 1.0, v13
	v_rcp_f32_e32 v109, v13
	v_cndmask_b32_e64 v13, 0, 32, vcc
	v_ldexp_f32 v10, v10, v13
	v_log_f32_e32 v10, v10
	v_fmac_f32_e32 v11, v109, v111
	s_add_u32 s15, s88, s16
	s_addc_u32 s16, s89, s17
	v_mul_f32_e32 v13, 0x3f317217, v10
	v_fma_f32 v13, v10, s29, -v13
	v_fmac_f32_e32 v13, 0x3377d1cf, v10
	v_fmac_f32_e32 v13, 0x3f317217, v10
	v_cmp_lt_f32_e64 s[58:59], |v10|, s30
	s_lshl_b32 s14, s14, 15
	s_add_u32 s14, s15, s14
	v_cndmask_b32_e64 v10, v10, v13, s[58:59]
	v_cndmask_b32_e32 v13, 0, v190, vcc
	v_cmp_gt_f32_e32 vcc, s28, v11
	v_sub_f32_e32 v10, v10, v13
	s_addc_u32 s15, s16, 0
	v_cndmask_b32_e64 v13, 0, 32, vcc
	v_ldexp_f32 v11, v11, v13
	v_log_f32_e32 v11, v11
	v_mov_b32_e32 v125, v145
	v_mul_f32_e32 v13, 0x3f317217, v11
	v_fma_f32 v13, v11, s29, -v13
	v_fmac_f32_e32 v13, 0x3377d1cf, v11
	v_fmac_f32_e32 v13, 0x3f317217, v11
	v_cmp_lt_f32_e64 s[58:59], |v11|, s30
	s_nop 1
	v_cndmask_b32_e64 v11, v11, v13, s[58:59]
	v_cndmask_b32_e32 v13, 0, v190, vcc
	v_sub_f32_e32 v11, v11, v13
	v_mul_f32_e32 v13, 0xbfb8aa3b, v17
	v_exp_f32_e32 v13, v13
	s_nop 0
	v_add_f32_e32 v13, 1.0, v13
	v_rcp_f32_e32 v112, v13
	v_mul_f32_e32 v13, 0xbfb8aa3b, v18
	v_exp_f32_e32 v13, v13
	v_fma_f32 v4, v112, v114, v4
	v_cmp_gt_f32_e32 vcc, s28, v4
	v_add_f32_e32 v13, 1.0, v13
	v_rcp_f32_e32 v113, v13
	v_cndmask_b32_e64 v13, 0, 32, vcc
	v_ldexp_f32 v4, v4, v13
	v_log_f32_e32 v4, v4
	v_fma_f32 v5, v113, v115, v5
	v_mul_f32_e32 v13, 0x3f317217, v4
	v_fma_f32 v13, v4, s29, -v13
	v_fmac_f32_e32 v13, 0x3377d1cf, v4
	v_fmac_f32_e32 v13, 0x3f317217, v4
	v_cmp_lt_f32_e64 s[58:59], |v4|, s30
	s_nop 1
	v_cndmask_b32_e64 v4, v4, v13, s[58:59]
	v_cndmask_b32_e32 v13, 0, v190, vcc
	v_cmp_gt_f32_e32 vcc, s28, v5
	v_sub_f32_e32 v4, v4, v13
	s_nop 0
	v_cndmask_b32_e64 v13, 0, 32, vcc
	v_ldexp_f32 v5, v5, v13
	v_log_f32_e32 v5, v5
	s_nop 0
	v_mul_f32_e32 v13, 0x3f317217, v5
	v_fma_f32 v13, v5, s29, -v13
	v_fmac_f32_e32 v13, 0x3377d1cf, v5
	v_fmac_f32_e32 v13, 0x3f317217, v5
	v_cmp_lt_f32_e64 s[58:59], |v5|, s30
	s_nop 1
	v_cndmask_b32_e64 v5, v5, v13, s[58:59]
	v_cndmask_b32_e32 v13, 0, v190, vcc
	v_sub_f32_e32 v5, v5, v13
	v_mul_f32_e32 v13, 0xbfb8aa3b, v19
	v_exp_f32_e32 v13, v13
	s_nop 0
	v_add_f32_e32 v13, 1.0, v13
	v_rcp_f32_e32 v136, v13
	v_mul_f32_e32 v13, 0xbfb8aa3b, v20
	v_exp_f32_e32 v13, v13
	v_fma_f32 v6, v136, v138, v6
	v_cmp_gt_f32_e32 vcc, s28, v6
	v_add_f32_e32 v13, 1.0, v13
	v_rcp_f32_e32 v137, v13
	v_cndmask_b32_e64 v13, 0, 32, vcc
	v_ldexp_f32 v6, v6, v13
	v_log_f32_e32 v6, v6
	v_fmac_f32_e32 v7, v137, v139
	v_mul_f32_e32 v13, 0x3f317217, v6
	v_fma_f32 v13, v6, s29, -v13
	v_fmac_f32_e32 v13, 0x3377d1cf, v6
	v_fmac_f32_e32 v13, 0x3f317217, v6
	v_cmp_lt_f32_e64 s[58:59], |v6|, s30
	s_nop 1
	v_cndmask_b32_e64 v6, v6, v13, s[58:59]
	v_cndmask_b32_e32 v13, 0, v190, vcc
	v_cmp_gt_f32_e32 vcc, s28, v7
	v_sub_f32_e32 v6, v6, v13
	s_nop 0
	v_cndmask_b32_e64 v13, 0, 32, vcc
	v_ldexp_f32 v7, v7, v13
	v_log_f32_e32 v7, v7
	s_nop 0
	v_mul_f32_e32 v13, 0x3f317217, v7
	v_fma_f32 v13, v7, s29, -v13
	v_fmac_f32_e32 v13, 0x3377d1cf, v7
	v_fmac_f32_e32 v13, 0x3f317217, v7
	v_cmp_lt_f32_e64 s[58:59], |v7|, s30
	s_nop 1
	v_cndmask_b32_e64 v7, v7, v13, s[58:59]
	v_cndmask_b32_e32 v13, 0, v190, vcc
	v_sub_f32_e32 v7, v7, v13
	ds_write_b128 v172, v[8:11]
	ds_write_b128 v172, v[4:7] offset:16
	v_lshlrev_b32_e32 v8, 16, v0
	v_mul_f32_e32 v8, 0xbfb8aa3b, v8
	v_exp_f32_e32 v8, v8
	v_and_b32_e32 v9, 0xffff0000, v0
	v_lshlrev_b32_e32 v10, 16, v1
	v_and_b32_e32 v11, 0xffff0000, v1
	v_lshlrev_b32_e32 v13, 16, v2
	ds_read_b128 v[4:7], v12
	ds_read_b128 v[0:3], v12 offset:16
	v_add_f32_e32 v8, 1.0, v8
	v_rcp_f32_e32 v140, v8
	v_mul_f32_e32 v8, 0xbfb8aa3b, v9
	v_exp_f32_e32 v8, v8
	s_waitcnt lgkmcnt(1)
; #define LAS __attribute__((address_space(3)))
; __device__ __forceinline__ float bflo(unsigned u) { return __uint_as_float(u << 16); }
; __device__ __forceinline__ float bfhi(unsigned u) { return __uint_as_float(u & 0xffff0000u); }
; __device__ __forceinline__ float sigm(float x) { return frcp(1.f + fexp(-x)); }
; __device__ __forceinline__ void hgrn_stepA(const Args& a, int l, LAS unsigned char* lds, int tid, int hh, const HIn& in, float (&kf)[16]) {
;     ...
;     for (int ii = 0; ii < 2; ++ii) {
;         const int cid = tid + 512 * ii, t = cid >> 4, d0 = (cid & 15) * 8;
;         const u32x4 u = in.f[ii];
;         float fl[8] = {bflo(u.x), bfhi(u.x), bflo(u.y), bfhi(u.y), bflo(u.z), bfhi(u.z), bflo(u.w), bfhi(u.w)};
;         float lf[8];
;         const LAS float* LB = (const LAS float*)(lds + 106496) + hh * 128 + d0; const f32x4 lb0 = *(const LAS f32x4*)LB, lb1 = *(const LAS f32x4*)(LB + 4);
;         const float lbv[8] = {lb0.x, lb0.y, lb0.z, lb0.w, lb1.x, lb1.y, lb1.z, lb1.w};
; #pragma unroll
;         for (int i = 0; i < 8; ++i) { const float lb = lbv[i]; const float sg = sigm(fl[i]);
;             const float f = lb + (1.f - lb) * sg; lf[i] = __logf(f); kf[ii * 8 + i] = (1.f - lb) * (1.f - sg); }
;         *(LAS f32x4*)(LF + t * 128 + d0) = (f32x4){lf[0], lf[1], lf[2], lf[3]}; *(LAS f32x4*)(LF + t * 128 + d0 + 4) = (f32x4){lf[4], lf[5], lf[6], lf[7]};
; __device__ __forceinline__ void hgrn_stage3_unit(const Args& a, int l, LAS unsigned char* lds, int tid, int u, const HIn& in, HIn& nxt, int unext) {
;     ...
;     const bf16_t* ST = (const bf16_t*)(a.ws + WS_H) + ((size_t)bh * 32 + c) * 16384;
;     bf16x8 stf[4][4]; u32x2 zz[4];
; #pragma unroll
;     for (int ks = 0; ks < 4; ++ks)
; #pragma unroll
;         for (int v = 0; v < 4; ++v) stf[ks][v] = *(const bf16x8*)(ST + ((vh * 4 + v) * 16 + fr) * 128 + ks * 32 + fq * 8);
	v_pk_add_f32 v[142:143], v[4:5], 1.0 op_sel_hi:[1,0] neg_lo:[1,0] neg_hi:[1,0]
	v_pk_add_f32 v[162:163], v[6:7], 1.0 op_sel_hi:[1,0] neg_lo:[1,0] neg_hi:[1,0]
	v_fma_f32 v4, v140, v142, v4
	v_add_f32_e32 v8, 1.0, v8
	v_cmp_gt_f32_e32 vcc, s28, v4
	v_rcp_f32_e32 v141, v8
	s_waitcnt lgkmcnt(0)
	v_pk_add_f32 v[166:167], v[0:1], 1.0 op_sel_hi:[1,0] neg_lo:[1,0] neg_hi:[1,0]
	v_cndmask_b32_e64 v8, 0, 32, vcc
	v_ldexp_f32 v4, v4, v8
	v_log_f32_e32 v4, v4
	v_fma_f32 v5, v141, v143, v5
	v_pk_add_f32 v[158:159], v[2:3], 1.0 op_sel_hi:[1,0] neg_lo:[1,0] neg_hi:[1,0]
	v_mul_f32_e32 v8, 0x3f317217, v4
	v_fma_f32 v8, v4, s29, -v8
	v_fmac_f32_e32 v8, 0x3377d1cf, v4
	v_fmac_f32_e32 v8, 0x3f317217, v4
	v_cmp_lt_f32_e64 s[58:59], |v4|, s30
	s_nop 1
	v_cndmask_b32_e64 v4, v4, v8, s[58:59]
	v_cndmask_b32_e32 v8, 0, v190, vcc
	v_cmp_gt_f32_e32 vcc, s28, v5
	v_sub_f32_e32 v4, v4, v8
	s_nop 0
	v_cndmask_b32_e64 v8, 0, 32, vcc
	v_ldexp_f32 v5, v5, v8
	v_log_f32_e32 v5, v5
	s_nop 0
	v_mul_f32_e32 v8, 0x3f317217, v5
	v_fma_f32 v8, v5, s29, -v8
	v_fmac_f32_e32 v8, 0x3377d1cf, v5
	v_fmac_f32_e32 v8, 0x3f317217, v5
	v_cmp_lt_f32_e64 s[58:59], |v5|, s30
	s_nop 1
	v_cndmask_b32_e64 v5, v5, v8, s[58:59]
	v_cndmask_b32_e32 v8, 0, v190, vcc
	v_sub_f32_e32 v5, v5, v8
	v_mul_f32_e32 v8, 0xbfb8aa3b, v10
	v_exp_f32_e32 v8, v8
	s_nop 0
	v_add_f32_e32 v8, 1.0, v8
	v_rcp_f32_e32 v160, v8
	v_mul_f32_e32 v8, 0xbfb8aa3b, v11
	v_exp_f32_e32 v8, v8
	v_fma_f32 v6, v160, v162, v6
	v_cmp_gt_f32_e32 vcc, s28, v6
	v_add_f32_e32 v8, 1.0, v8
	v_rcp_f32_e32 v161, v8
	v_cndmask_b32_e64 v8, 0, 32, vcc
	v_ldexp_f32 v6, v6, v8
	v_log_f32_e32 v6, v6
	v_fmac_f32_e32 v7, v161, v163
	v_mul_f32_e32 v8, 0x3f317217, v6
	v_fma_f32 v8, v6, s29, -v8
	v_fmac_f32_e32 v8, 0x3377d1cf, v6
	v_fmac_f32_e32 v8, 0x3f317217, v6
	v_cmp_lt_f32_e64 s[58:59], |v6|, s30
	s_nop 1
	v_cndmask_b32_e64 v6, v6, v8, s[58:59]
	v_cndmask_b32_e32 v8, 0, v190, vcc
	v_cmp_gt_f32_e32 vcc, s28, v7
	v_sub_f32_e32 v6, v6, v8
	s_nop 0
	v_cndmask_b32_e64 v8, 0, 32, vcc
	v_ldexp_f32 v7, v7, v8
	v_log_f32_e32 v7, v7
	s_nop 0
	v_mul_f32_e32 v8, 0x3f317217, v7
	v_fma_f32 v8, v7, s29, -v8
	v_fmac_f32_e32 v8, 0x3377d1cf, v7
	v_fmac_f32_e32 v8, 0x3f317217, v7
	v_cmp_lt_f32_e64 s[58:59], |v7|, s30
	s_nop 1
	v_cndmask_b32_e64 v7, v7, v8, s[58:59]
	v_cndmask_b32_e32 v8, 0, v190, vcc
	v_sub_f32_e32 v7, v7, v8
	v_mul_f32_e32 v8, 0xbfb8aa3b, v13
	v_exp_f32_e32 v8, v8
	s_nop 0
	v_add_f32_e32 v8, 1.0, v8
	v_rcp_f32_e32 v164, v8
	v_mul_f32_e32 v8, 0xbfb8aa3b, v14
	v_exp_f32_e32 v8, v8
	v_fma_f32 v0, v164, v166, v0
	v_cmp_gt_f32_e32 vcc, s28, v0
	v_add_f32_e32 v8, 1.0, v8
	v_rcp_f32_e32 v165, v8
	v_cndmask_b32_e64 v8, 0, 32, vcc
	v_ldexp_f32 v0, v0, v8
	v_log_f32_e32 v0, v0
	v_fma_f32 v1, v165, v167, v1
	v_mul_f32_e32 v8, 0x3f317217, v0
	v_fma_f32 v8, v0, s29, -v8
	v_fmac_f32_e32 v8, 0x3377d1cf, v0
	v_fmac_f32_e32 v8, 0x3f317217, v0
	v_cmp_lt_f32_e64 s[58:59], |v0|, s30
	s_nop 1
	v_cndmask_b32_e64 v0, v0, v8, s[58:59]
	v_cndmask_b32_e32 v8, 0, v190, vcc
	v_cmp_gt_f32_e32 vcc, s28, v1
	v_sub_f32_e32 v0, v0, v8
	s_nop 0
	v_cndmask_b32_e64 v8, 0, 32, vcc
	v_ldexp_f32 v1, v1, v8
	v_log_f32_e32 v1, v1
	s_nop 0
	v_mul_f32_e32 v8, 0x3f317217, v1
	v_fma_f32 v8, v1, s29, -v8
	v_fmac_f32_e32 v8, 0x3377d1cf, v1
	v_fmac_f32_e32 v8, 0x3f317217, v1
	v_cmp_lt_f32_e64 s[58:59], |v1|, s30
	s_nop 1
	v_cndmask_b32_e64 v1, v1, v8, s[58:59]
	v_cndmask_b32_e32 v8, 0, v190, vcc
	v_sub_f32_e32 v1, v1, v8
	v_mul_f32_e32 v8, 0xbfb8aa3b, v15
	v_exp_f32_e32 v8, v8
	s_nop 0
	v_add_f32_e32 v8, 1.0, v8
	v_rcp_f32_e32 v156, v8
	v_mul_f32_e32 v8, 0xbfb8aa3b, v16
	v_exp_f32_e32 v8, v8
	v_fma_f32 v2, v156, v158, v2
	v_cmp_gt_f32_e32 vcc, s28, v2
	v_add_f32_e32 v8, 1.0, v8
	v_rcp_f32_e32 v157, v8
	v_cndmask_b32_e64 v8, 0, 32, vcc
	v_ldexp_f32 v2, v2, v8
	v_log_f32_e32 v2, v2
	v_fmac_f32_e32 v3, v157, v159
	v_mul_f32_e32 v8, 0x3f317217, v2
	v_fma_f32 v8, v2, s29, -v8
	v_fmac_f32_e32 v8, 0x3377d1cf, v2
	v_fmac_f32_e32 v8, 0x3f317217, v2
	v_cmp_lt_f32_e64 s[58:59], |v2|, s30
	s_nop 1
	v_cndmask_b32_e64 v2, v2, v8, s[58:59]
	v_cndmask_b32_e32 v8, 0, v190, vcc
	v_cmp_gt_f32_e32 vcc, s28, v3
	v_sub_f32_e32 v2, v2, v8
	s_nop 0
	v_cndmask_b32_e64 v8, 0, 32, vcc
	v_ldexp_f32 v3, v3, v8
	v_log_f32_e32 v3, v3
	s_nop 0
	v_mul_f32_e32 v8, 0x3f317217, v3
	v_fma_f32 v8, v3, s29, -v8
	v_fmac_f32_e32 v8, 0x3377d1cf, v3
	v_fmac_f32_e32 v8, 0x3f317217, v3
	v_cmp_lt_f32_e64 s[58:59], |v3|, s30
	s_nop 1
	v_cndmask_b32_e64 v3, v3, v8, s[58:59]
	v_cndmask_b32_e32 v8, 0, v190, vcc
	v_sub_f32_e32 v3, v3, v8
	ds_write_b128 v172, v[4:7] offset:16384
	ds_write_b128 v172, v[0:3] offset:16400
	v_lshlrev_b32_e32 v14, 3, v120
	s_mov_b64 s[16:17], 0x400
	s_mov_b64 s[18:19], 0x800
	v_lshl_or_b32 v2, s36, 13, v14
	v_or_b32_e32 v6, 0x800, v2
	v_ashrrev_i32_e32 v7, 31, v6
	v_lshl_add_u64 v[0:1], v[144:145], 4, s[14:15]
	v_lshlrev_b64 v[6:7], 1, v[6:7]
	v_lshl_add_u64 v[8:9], v[0:1], 0, v[6:7]
	v_ashrrev_i32_e32 v3, 31, v2
	global_load_dwordx4 v[60:63], v[8:9], off
; #define LAS __attribute__((address_space(3)))
; #define BAR_LDS() do { asm volatile("s_waitcnt lgkmcnt(0)" ::: "memory"); __builtin_amdgcn_s_barrier(); asm volatile("" ::: "memory"); } while (0)
; __device__ __forceinline__ void hgrn_cumsum_scan(LAS unsigned char* lds, int tid) {
;     LAS float* LF = (LAS float*)lds;
;     LAS float* PT = (LAS float*)(lds + 32768);
;     BAR_LDS();
;     const int d = tid & 127, pt = tid >> 7;
;     float v[16];
; #pragma unroll
;     for (int t = 0; t < 16; ++t) v[t] = LF[(pt * 16 + t) * 128 + d];
; #pragma unroll
;     for (int t = 1; t < 16; ++t) v[t] += v[t - 1];
;     PT[pt * 128 + d] = v[15];
;     BAR_LDS();
;     { float off = 0.f;
; #pragma unroll
;       for (int p = 0; p < 3; ++p) off += (p < pt) ? PT[p * 128 + d] : 0.f;
; #pragma unroll
;       for (int t = 0; t < 16; ++t) LF[(pt * 16 + t) * 128 + d] = v[t] + off; }
; __device__ __forceinline__ void hgrn_stage3_unit(const Args& a, int l, LAS unsigned char* lds, int tid, int u, const HIn& in, HIn& nxt, int unext) {
;     ...
;     const bf16_t* ST = (const bf16_t*)(a.ws + WS_H) + ((size_t)bh * 32 + c) * 16384;
;     bf16x8 stf[4][4]; u32x2 zz[4];
; #pragma unroll
;     for (int ks = 0; ks < 4; ++ks)
; #pragma unroll
;         for (int v = 0; v < 4; ++v) stf[ks][v] = *(const bf16x8*)(ST + ((vh * 4 + v) * 16 + fr) * 128 + ks * 32 + fq * 8);
; #pragma unroll
;     for (int v = 0; v < 4; ++v) zz[v] = *(const u32x2*)(proj + row * NCOL + CZ + 512 + hh * 128 + (vh * 4 + v) * 16 + fq * 4);
;     hgrn_load<true>(a, tid, unext, nxt);
;     hgrn_cumsum_scan(lds, tid);
	v_or_b32_e32 v8, 0x1000, v2
	v_lshl_add_u64 v[4:5], v[2:3], 1, v[0:1]
	v_ashrrev_i32_e32 v9, 31, v8
	v_or_b32_e32 v2, 0x1800, v2
	v_lshlrev_b64 v[8:9], 1, v[8:9]
	v_ashrrev_i32_e32 v3, 31, v2
	v_lshl_add_u64 v[10:11], v[0:1], 0, v[8:9]
	v_lshlrev_b64 v[2:3], 1, v[2:3]
	global_load_dwordx4 v[92:95], v[10:11], off
	v_lshl_add_u64 v[10:11], v[0:1], 0, v[2:3]
	global_load_dwordx4 v[96:99], v[10:11], off
	v_lshl_add_u64 v[10:11], v[0:1], 0, s[16:17]
	v_lshl_add_u64 v[12:13], v[10:11], 0, v[6:7]
	global_load_dwordx4 v[40:43], v[12:13], off
	v_lshl_add_u64 v[12:13], v[10:11], 0, v[8:9]
	v_lshl_add_u64 v[10:11], v[10:11], 0, v[2:3]
	global_load_dwordx4 v[44:47], v[12:13], off
	global_load_dwordx4 v[52:55], v[10:11], off
	v_lshl_add_u64 v[10:11], v[0:1], 0, s[18:19]
	s_mov_b64 s[14:15], 0xc00
	v_lshl_add_u64 v[12:13], v[10:11], 0, v[6:7]
	v_lshl_add_u64 v[0:1], v[0:1], 0, s[14:15]
	s_lshl_b64 s[14:15], s[40:41], 11
	global_load_dwordx4 v[36:39], v[4:5], off
	global_load_dwordx4 v[32:35], v[4:5], off offset:1024
	global_load_dwordx4 v[56:59], v[4:5], off offset:2048
	global_load_dwordx4 v[48:51], v[4:5], off offset:3072
	global_load_dwordx4 v[76:79], v[12:13], off
	v_lshl_add_u64 v[12:13], v[10:11], 0, v[8:9]
	v_lshl_add_u64 v[10:11], v[10:11], 0, v[2:3]
	v_lshl_add_u64 v[4:5], v[0:1], 0, v[6:7]
	s_or_b32 s6, s14, s6
	global_load_dwordx4 v[88:91], v[10:11], off
	global_load_dwordx4 v[64:67], v[4:5], off
	v_lshl_add_u64 v[4:5], v[0:1], 0, v[8:9]
	v_lshl_add_u64 v[0:1], v[0:1], 0, v[2:3]
	s_or_b32 s6, s6, s4
	global_load_dwordx4 v[68:71], v[4:5], off
	global_load_dwordx4 v[80:83], v[0:1], off
	v_mov_b32_e32 v1, s15
	v_or_b32_e32 v0, s6, v120
	v_lshlrev_b64 v[0:1], 13, v[0:1]
	v_lshl_add_u64 v[134:135], s[84:85], 0, v[0:1]
	s_lshl_b32 s6, s9, 8
	v_lshl_add_u64 v[0:1], v[134:135], 0, s[6:7]
	s_lshl_b32 s40, s36, 6
	v_lshlrev_b32_e32 v2, 1, v122
	v_mov_b32_e32 v3, v145
	v_lshl_add_u64 v[0:1], v[0:1], 0, v[2:3]
	s_ashr_i32 s41, s40, 31
	s_ashr_i32 s14, s5, 7
	v_lshl_add_u64 v[0:1], s[40:41], 1, v[0:1]
	s_ashr_i32 s15, s14, 31
	s_lshl_b32 s6, s5, 6
	v_lshl_add_u64 v[2:3], v[0:1], 0, s[12:13]
	v_add_co_u32_e32 v0, vcc, s26, v0
	s_lshl_b64 s[14:15], s[14:15], 11
	s_and_b32 s6, s6, 0x7c0
	v_addc_co_u32_e32 v1, vcc, 0, v1, vcc
	s_or_b32 s14, s14, s6
	global_load_dwordx4 v[84:87], v[12:13], off
	global_load_dwordx2 v[132:133], v[0:1], off
	global_load_dwordx2 v[130:131], v[2:3], off offset:32
	global_load_dwordx2 v[128:129], v[2:3], off offset:64
	global_load_dwordx2 v[126:127], v[2:3], off offset:96
	v_lshl_add_u64 v[0:1], s[14:15], 0, v[116:117]
	v_lshlrev_b64 v[0:1], 13, v[0:1]
	s_lshl_b32 s5, s5, 3
	v_lshl_add_u64 v[0:1], s[84:85], 0, v[0:1]
	s_and_b32 s6, s5, 0x300
	v_lshl_add_u64 v[0:1], v[0:1], 0, s[6:7]
	v_lshl_add_u64 v[0:1], v[0:1], 0, v[124:125]
	v_add_co_u32_e32 v2, vcc, s26, v0
	s_nop 1
	v_addc_co_u32_e32 v3, vcc, 0, v1, vcc
	global_load_dwordx4 v[4:7], v[2:3], off offset:2048
	global_load_dwordx4 v[8:11], v[2:3], off offset:3072
	global_load_dwordx4 v[12:15], v[0:1], off offset:1024
	v_lshl_add_u64 v[0:1], s[14:15], 0, v[118:119]
	v_lshlrev_b64 v[0:1], 13, v[0:1]
	v_lshl_add_u64 v[0:1], s[84:85], 0, v[0:1]
	v_lshl_add_u64 v[0:1], v[0:1], 0, s[6:7]
	v_lshl_add_u64 v[20:21], v[0:1], 0, v[124:125]
	v_add_co_u32_e32 v16, vcc, s26, v20
	s_nop 1
	v_addc_co_u32_e32 v17, vcc, 0, v21, vcc
	global_load_dwordx4 v[0:3], v[16:17], off offset:2048
	s_nop 0
	global_load_dwordx4 v[16:19], v[16:17], off offset:3072
	s_nop 0
	global_load_dwordx4 v[20:23], v[20:21], off offset:1024
	s_waitcnt lgkmcnt(0)
	s_barrier
	ds_read2st64_b32 v[168:169], v175 offset1:2
	ds_read2st64_b32 v[206:207], v175 offset0:4 offset1:6
	ds_read2st64_b32 v[208:209], v175 offset0:8 offset1:10
	ds_read2st64_b32 v[218:219], v175 offset0:12 offset1:14
	ds_read2st64_b32 v[220:221], v175 offset0:16 offset1:18
	ds_read2st64_b32 v[222:223], v175 offset0:20 offset1:22
	ds_read2st64_b32 v[224:225], v175 offset0:24 offset1:26
	ds_read2st64_b32 v[226:227], v175 offset0:28 offset1:30
	s_waitcnt lgkmcnt(7)
	v_add_f32_e32 v217, v168, v169
	s_waitcnt lgkmcnt(6)
	v_add_f32_e32 v215, v206, v217
	v_add_f32_e32 v216, v207, v215
	s_waitcnt lgkmcnt(5)
	v_add_f32_e32 v213, v208, v216
	v_add_f32_e32 v214, v209, v213
	s_waitcnt lgkmcnt(4)
	v_add_f32_e32 v211, v218, v214
	v_add_f32_e32 v212, v219, v211
	s_waitcnt lgkmcnt(3)
	v_add_f32_e32 v209, v220, v212
	v_add_f32_e32 v210, v221, v209
	s_waitcnt lgkmcnt(2)
	v_add_f32_e32 v207, v222, v210
	v_add_f32_e32 v208, v223, v207
	s_waitcnt lgkmcnt(1)
	v_add_f32_e32 v205, v224, v208
	v_add_f32_e32 v206, v225, v205
	s_waitcnt lgkmcnt(0)
	v_add_f32_e32 v125, v226, v206
	v_add_f32_e32 v169, v227, v125
	ds_write_b32 v123, v169 offset:32768
	s_waitcnt lgkmcnt(0)
	s_barrier
	v_mov_b32_e32 v218, 0
	v_mov_b32_e32 v219, 0
	s_and_saveexec_b64 s[14:15], s[42:43]
	s_cbranch_execnz .LBB0_654
	s_or_b64 exec, exec, s[14:15]
	v_mov_b32_e32 v220, 0
	s_and_saveexec_b64 s[14:15], s[44:45]
	s_cbranch_execnz .LBB0_655

; #define SEAM(k) do { if (IN(k) && IN((k) + 1)) { if (a.pad == 0x5eed) cg::this_grid().sync(); xcd_barrier(xbar); } } while (0)
; __global__ void __launch_bounds__(512) hymba_fwd(Args a) {
;     ...
;         if (l == 0) SEAM(base + 4);
.LBB0_680:
	v_readlane_b32 s4, v244, 60
	v_readlane_b32 s8, v246, 0
	s_add_i32 s4, s4, 5
	v_readlane_b32 s9, v246, 1
	s_cmp_ge_i32 s4, s9
	s_barrier
	s_cbranch_scc1 .LBB0_742
	s_cmp_eq_u32 s3, 0x100
	s_cbranch_scc1 .Lbbsb3
	s_and_b64 vcc, exec, s[96:97]
	s_cbranch_vccnz .LBB0_693
	s_barrier
	s_mov_b64 s[14:15], exec
	v_readlane_b32 s8, v244, 4
	v_readlane_b32 s9, v244, 5
	s_and_b64 s[8:9], s[14:15], s[8:9]
	s_mov_b64 exec, s[8:9]
	s_cbranch_execz .LBB0_692
	v_readlane_b32 s8, v246, 2
	v_readlane_b32 s9, v246, 3
	buffer_wbl2 sc1
	s_waitcnt vmcnt(0)
	s_load_dwordx2 s[16:17], s[8:9], 0x58
	s_mov_b64 s[18:19], exec
	v_mbcnt_lo_u32_b32 v1, s18, 0
	v_mbcnt_hi_u32_b32 v1, s19, v1
	v_cmp_eq_u32_e32 vcc, 0, v1
	s_waitcnt lgkmcnt(0)
	global_load_dword v0, v145, s[16:17] offset:40
	s_and_saveexec_b64 s[40:41], vcc
	s_cbranch_execz .LBB0_685
	s_bcnt1_i32_b64 s5, s[18:19]
	v_mov_b32_e32 v2, s5
	global_atomic_add v2, v145, v2, s[16:17] offset:32 sc0

; __device__ __forceinline__ unsigned pk2(float lo, float hi) { f32x2_t v = {lo, hi}; bf16x2_t b = __builtin_convertvector(v, bf16x2_t); return __builtin_bit_cast(unsigned, b); }
; __device__ __forceinline__ float bflo(unsigned u) { return __uint_as_float(u << 16); }
; __device__ __forceinline__ float bfhi(unsigned u) { return __uint_as_float(u & 0xffff0000u); }
; __device__ __forceinline__ int otid() { int t = threadIdx.x; asm volatile("" : "+v"(t)); return t; }
; __device__ __forceinline__ void hgrn_scan_phase(const Args& a) {
;     const int id = blockIdx.x * 512 + otid(), NT = gridDim.x * 512;
;     for (int it = id; it < 32 * 128 * 32; it += NT) {
;         const int bh = it >> 12, dv = (it >> 5) & 127, dkc = it & 31;
;         u32x2* st = (u32x2*)((bf16_t*)(a.ws + WS_H) + (size_t)bh * 32 * 16384 + dv * 128 + dkc * 4);
;         const f32x4* dc = (const f32x4*)((const float*)(a.ws + WS_DECAY) + (size_t)bh * 32 * 128 + dkc * 4);
;         float r0 = 0.f, r1 = 0.f, r2 = 0.f, r3 = 0.f;
; #pragma unroll 8
;         for (int c = 0; c < 32; ++c) {
;             const u32x2 u = st[(size_t)c * 4096]; const f32x4 dd = dc[c * 32];
;             u32x2 o; o.x = pk2(r0, r1); o.y = pk2(r2, r3); st[(size_t)c * 4096] = o;
;             r0 = dd.x * r0 + bflo(u.x); r1 = dd.y * r1 + bfhi(u.x); r2 = dd.z * r2 + bflo(u.y); r3 = dd.w * r3 + bfhi(u.y);
;         }
;     }
.Lscan_fast:
	s_and_b32 s4, s2, 7
	s_lshl_b32 s4, s4, 2
	s_lshr_b32 s8, s2, 6
	s_add_i32 s4, s4, s8
	s_lshl_b32 s4, s4, 12
	s_bfe_u32 s8, s2, 0x30003
	s_lshl_b32 s8, s8, 9
	s_or_b32 s4, s4, s8
	v_or_b32_e32 v12, s4, v178
	v_lshrrev_b32_e32 v222, 12, v12
	v_and_b32_e32 v220, 0xfff, v12
	v_bfe_u32 v221, v12, 5, 4
	v_and_b32_e32 v216, 1, v12
	v_lshl_or_b32 v221, v221, 1, v216
	v_lshlrev_b32_e32 v220, 3, v220
	v_lshlrev_b32_e32 v221, 4, v221
	v_lshl_or_b32 v220, v222, 20, v220
	v_lshl_or_b32 v221, v222, 14, v221
	s_add_u32 s10, s78, 0x1e00000
	s_addc_u32 s11, s79, 0
	s_mov_b32 s14, s10
	s_mov_b32 s15, s11
	s_add_u32 s8, s78, 0xf620000
	s_addc_u32 s9, s79, 0
	v_mov_b32_e32 v208, 0
	v_mov_b32_e32 v209, 0
	v_mov_b32_e32 v210, 0
	v_mov_b32_e32 v211, 0
	global_load_dwordx2 v[128:129], v220, s[10:11]
	s_add_u32 s10, s10, 0x8000
	s_addc_u32 s11, s11, 0
	global_load_dwordx4 v[12:15], v221, s[8:9]
	global_load_dwordx2 v[130:131], v220, s[10:11]
	s_add_u32 s10, s10, 0x8000
	s_addc_u32 s11, s11, 0
	global_load_dwordx4 v[16:19], v221, s[8:9] offset:512
	global_load_dwordx2 v[132:133], v220, s[10:11]
	s_add_u32 s10, s10, 0x8000
	s_addc_u32 s11, s11, 0
	global_load_dwordx4 v[20:23], v221, s[8:9] offset:1024
	global_load_dwordx2 v[134:135], v220, s[10:11]
	s_add_u32 s10, s10, 0x8000
	s_addc_u32 s11, s11, 0
	global_load_dwordx4 v[24:27], v221, s[8:9] offset:1536
	global_load_dwordx2 v[136:137], v220, s[10:11]
	s_add_u32 s10, s10, 0x8000
	s_addc_u32 s11, s11, 0
	global_load_dwordx4 v[28:31], v221, s[8:9] offset:2048
	global_load_dwordx2 v[138:139], v220, s[10:11]
	s_add_u32 s10, s10, 0x8000
	s_addc_u32 s11, s11, 0
	global_load_dwordx4 v[32:35], v221, s[8:9] offset:2560
	global_load_dwordx2 v[140:141], v220, s[10:11]
	s_add_u32 s10, s10, 0x8000
	s_addc_u32 s11, s11, 0
	global_load_dwordx4 v[36:39], v221, s[8:9] offset:3072
	global_load_dwordx2 v[142:143], v220, s[10:11]
	s_add_u32 s10, s10, 0x8000
	s_addc_u32 s11, s11, 0
	global_load_dwordx4 v[40:43], v221, s[8:9] offset:3584
	s_add_u32 s8, s8, 0x1000
	s_addc_u32 s9, s9, 0
	global_load_dwordx2 v[156:157], v220, s[10:11]
	s_add_u32 s10, s10, 0x8000
	s_addc_u32 s11, s11, 0
	global_load_dwordx4 v[44:47], v221, s[8:9]
	global_load_dwordx2 v[158:159], v220, s[10:11]
	s_add_u32 s10, s10, 0x8000
	s_addc_u32 s11, s11, 0
	global_load_dwordx4 v[48:51], v221, s[8:9] offset:512
	global_load_dwordx2 v[160:161], v220, s[10:11]
	s_add_u32 s10, s10, 0x8000
	s_addc_u32 s11, s11, 0
	global_load_dwordx4 v[52:55], v221, s[8:9] offset:1024
	global_load_dwordx2 v[162:163], v220, s[10:11]
	s_add_u32 s10, s10, 0x8000
	s_addc_u32 s11, s11, 0
	global_load_dwordx4 v[56:59], v221, s[8:9] offset:1536
	global_load_dwordx2 v[164:165], v220, s[10:11]
	s_add_u32 s10, s10, 0x8000
	s_addc_u32 s11, s11, 0
	global_load_dwordx4 v[60:63], v221, s[8:9] offset:2048
	global_load_dwordx2 v[166:167], v220, s[10:11]
	s_add_u32 s10, s10, 0x8000
	s_addc_u32 s11, s11, 0
	global_load_dwordx4 v[64:67], v221, s[8:9] offset:2560
	global_load_dwordx2 v[168:169], v220, s[10:11]
	s_add_u32 s10, s10, 0x8000
	s_addc_u32 s11, s11, 0
	global_load_dwordx4 v[68:71], v221, s[8:9] offset:3072
	global_load_dwordx2 v[172:173], v220, s[10:11]
	s_add_u32 s10, s10, 0x8000
	s_addc_u32 s11, s11, 0
	global_load_dwordx4 v[72:75], v221, s[8:9] offset:3584
	s_add_u32 s8, s8, 0x1000
	s_addc_u32 s9, s9, 0
	global_load_dwordx2 v[174:175], v220, s[10:11]
	s_add_u32 s10, s10, 0x8000
	s_addc_u32 s11, s11, 0
	global_load_dwordx4 v[76:79], v221, s[8:9]
	global_load_dwordx2 v[224:225], v220, s[10:11]
	s_add_u32 s10, s10, 0x8000
	s_addc_u32 s11, s11, 0
	global_load_dwordx4 v[84:87], v221, s[8:9] offset:512
	global_load_dwordx2 v[200:201], v220, s[10:11]
	s_add_u32 s10, s10, 0x8000
	s_addc_u32 s11, s11, 0
	global_load_dwordx4 v[88:91], v221, s[8:9] offset:1024
	global_load_dwordx2 v[202:203], v220, s[10:11]
	s_add_u32 s10, s10, 0x8000
	s_addc_u32 s11, s11, 0
	global_load_dwordx4 v[92:95], v221, s[8:9] offset:1536
	global_load_dwordx2 v[204:205], v220, s[10:11]
	s_add_u32 s10, s10, 0x8000
	s_addc_u32 s11, s11, 0
	global_load_dwordx4 v[100:103], v221, s[8:9] offset:2048
	global_load_dwordx2 v[206:207], v220, s[10:11]
	s_add_u32 s10, s10, 0x8000
	s_addc_u32 s11, s11, 0
	global_load_dwordx4 v[104:107], v221, s[8:9] offset:2560
	global_load_dwordx2 v[226:227], v220, s[10:11]
	s_add_u32 s10, s10, 0x8000
	s_addc_u32 s11, s11, 0
	global_load_dwordx4 v[108:111], v221, s[8:9] offset:3072
	global_load_dwordx2 v[228:229], v220, s[10:11]
	s_add_u32 s10, s10, 0x8000
	s_addc_u32 s11, s11, 0
	global_load_dwordx4 v[112:115], v221, s[8:9] offset:3584
	s_add_u32 s8, s8, 0x1000
	s_addc_u32 s9, s9, 0
	v_cvt_pk_bf16_f32 v216, v208, v209
	v_cvt_pk_bf16_f32 v217, v210, v211
	global_store_dwordx2 v220, v[216:217], s[14:15]
	s_add_u32 s14, s14, 0x8000
	s_addc_u32 s15, s15, 0
	s_waitcnt vmcnt(48)
	v_lshlrev_b32_e32 v212, 16, v128
	v_and_b32_e32 v213, 0xffff0000, v128
	v_lshlrev_b32_e32 v214, 16, v129
	v_and_b32_e32 v215, 0xffff0000, v129
	s_waitcnt vmcnt(47)
	v_pk_fma_f32 v[208:209], v[208:209], v[12:13], v[212:213]
	v_pk_fma_f32 v[210:211], v[210:211], v[14:15], v[214:215]
	global_load_dwordx2 v[128:129], v220, s[10:11]
	s_add_u32 s10, s10, 0x8000
	s_addc_u32 s11, s11, 0
	global_load_dwordx4 v[12:15], v221, s[8:9]
	v_cvt_pk_bf16_f32 v218, v208, v209
	v_cvt_pk_bf16_f32 v219, v210, v211
	global_store_dwordx2 v220, v[218:219], s[14:15]
	s_add_u32 s14, s14, 0x8000
	s_addc_u32 s15, s15, 0
	s_waitcnt vmcnt(49)
	v_lshlrev_b32_e32 v212, 16, v130
	v_and_b32_e32 v213, 0xffff0000, v130
	v_lshlrev_b32_e32 v214, 16, v131
	v_and_b32_e32 v215, 0xffff0000, v131
	s_waitcnt vmcnt(48)
; __device__ __forceinline__ unsigned pk2(float lo, float hi) { f32x2_t v = {lo, hi}; bf16x2_t b = __builtin_convertvector(v, bf16x2_t); return __builtin_bit_cast(unsigned, b); }
; __device__ __forceinline__ float bflo(unsigned u) { return __uint_as_float(u << 16); }
; __device__ __forceinline__ float bfhi(unsigned u) { return __uint_as_float(u & 0xffff0000u); }
; __device__ __forceinline__ void hgrn_scan_phase(const Args& a) {
;     ...
;         for (int c = 0; c < 32; ++c) {
;             const u32x2 u = st[(size_t)c * 4096]; const f32x4 dd = dc[c * 32];
;             u32x2 o; o.x = pk2(r0, r1); o.y = pk2(r2, r3); st[(size_t)c * 4096] = o;
;             r0 = dd.x * r0 + bflo(u.x); r1 = dd.y * r1 + bfhi(u.x); r2 = dd.z * r2 + bflo(u.y); r3 = dd.w * r3 + bfhi(u.y);
;         }
	v_pk_fma_f32 v[208:209], v[208:209], v[16:17], v[212:213]
	v_pk_fma_f32 v[210:211], v[210:211], v[18:19], v[214:215]
	global_load_dwordx2 v[130:131], v220, s[10:11]
	s_add_u32 s10, s10, 0x8000
	s_addc_u32 s11, s11, 0
	global_load_dwordx4 v[16:19], v221, s[8:9] offset:512
	v_cvt_pk_bf16_f32 v216, v208, v209
	v_cvt_pk_bf16_f32 v217, v210, v211
	global_store_dwordx2 v220, v[216:217], s[14:15]
	s_add_u32 s14, s14, 0x8000
	s_addc_u32 s15, s15, 0
	s_waitcnt vmcnt(50)
	v_lshlrev_b32_e32 v212, 16, v132
	v_and_b32_e32 v213, 0xffff0000, v132
	v_lshlrev_b32_e32 v214, 16, v133
	v_and_b32_e32 v215, 0xffff0000, v133
	s_waitcnt vmcnt(49)
	v_pk_fma_f32 v[208:209], v[208:209], v[20:21], v[212:213]
	v_pk_fma_f32 v[210:211], v[210:211], v[22:23], v[214:215]
	global_load_dwordx2 v[132:133], v220, s[10:11]
	s_add_u32 s10, s10, 0x8000
	s_addc_u32 s11, s11, 0
	global_load_dwordx4 v[20:23], v221, s[8:9] offset:1024
	v_cvt_pk_bf16_f32 v218, v208, v209
	v_cvt_pk_bf16_f32 v219, v210, v211
	global_store_dwordx2 v220, v[218:219], s[14:15]
	s_add_u32 s14, s14, 0x8000
	s_addc_u32 s15, s15, 0
	s_waitcnt vmcnt(51)
	v_lshlrev_b32_e32 v212, 16, v134
	v_and_b32_e32 v213, 0xffff0000, v134
	v_lshlrev_b32_e32 v214, 16, v135
	v_and_b32_e32 v215, 0xffff0000, v135
	s_waitcnt vmcnt(50)
	v_pk_fma_f32 v[208:209], v[208:209], v[24:25], v[212:213]
	v_pk_fma_f32 v[210:211], v[210:211], v[26:27], v[214:215]
	global_load_dwordx2 v[134:135], v220, s[10:11]
	s_add_u32 s10, s10, 0x8000
	s_addc_u32 s11, s11, 0
	global_load_dwordx4 v[24:27], v221, s[8:9] offset:1536
	v_cvt_pk_bf16_f32 v216, v208, v209
	v_cvt_pk_bf16_f32 v217, v210, v211
	global_store_dwordx2 v220, v[216:217], s[14:15]
	s_add_u32 s14, s14, 0x8000
	s_addc_u32 s15, s15, 0
	s_waitcnt vmcnt(52)
	v_lshlrev_b32_e32 v212, 16, v136
	v_and_b32_e32 v213, 0xffff0000, v136
	v_lshlrev_b32_e32 v214, 16, v137
	v_and_b32_e32 v215, 0xffff0000, v137
	s_waitcnt vmcnt(51)
	v_pk_fma_f32 v[208:209], v[208:209], v[28:29], v[212:213]
	v_pk_fma_f32 v[210:211], v[210:211], v[30:31], v[214:215]
	global_load_dwordx2 v[136:137], v220, s[10:11]
	s_add_u32 s10, s10, 0x8000
	s_addc_u32 s11, s11, 0
	global_load_dwordx4 v[28:31], v221, s[8:9] offset:2048
	v_cvt_pk_bf16_f32 v218, v208, v209
	v_cvt_pk_bf16_f32 v219, v210, v211
	global_store_dwordx2 v220, v[218:219], s[14:15]
	s_add_u32 s14, s14, 0x8000
	s_addc_u32 s15, s15, 0
	s_waitcnt vmcnt(53)
	v_lshlrev_b32_e32 v212, 16, v138
	v_and_b32_e32 v213, 0xffff0000, v138
	v_lshlrev_b32_e32 v214, 16, v139
	v_and_b32_e32 v215, 0xffff0000, v139
	s_waitcnt vmcnt(52)
	v_pk_fma_f32 v[208:209], v[208:209], v[32:33], v[212:213]
	v_pk_fma_f32 v[210:211], v[210:211], v[34:35], v[214:215]
	global_load_dwordx2 v[138:139], v220, s[10:11]
	s_add_u32 s10, s10, 0x8000
	s_addc_u32 s11, s11, 0
	global_load_dwordx4 v[32:35], v221, s[8:9] offset:2560
	v_cvt_pk_bf16_f32 v216, v208, v209
	v_cvt_pk_bf16_f32 v217, v210, v211
	global_store_dwordx2 v220, v[216:217], s[14:15]
	s_add_u32 s14, s14, 0x8000
	s_addc_u32 s15, s15, 0
	s_waitcnt vmcnt(54)
	v_lshlrev_b32_e32 v212, 16, v140
	v_and_b32_e32 v213, 0xffff0000, v140
	v_lshlrev_b32_e32 v214, 16, v141
	v_and_b32_e32 v215, 0xffff0000, v141
	s_waitcnt vmcnt(53)
	v_pk_fma_f32 v[208:209], v[208:209], v[36:37], v[212:213]
	v_pk_fma_f32 v[210:211], v[210:211], v[38:39], v[214:215]
	global_load_dwordx2 v[140:141], v220, s[10:11]
	s_add_u32 s10, s10, 0x8000
	s_addc_u32 s11, s11, 0
	global_load_dwordx4 v[36:39], v221, s[8:9] offset:3072
	v_cvt_pk_bf16_f32 v218, v208, v209
	v_cvt_pk_bf16_f32 v219, v210, v211
	global_store_dwordx2 v220, v[218:219], s[14:15]
	s_add_u32 s14, s14, 0x8000
	s_addc_u32 s15, s15, 0
	s_waitcnt vmcnt(55)
	v_lshlrev_b32_e32 v212, 16, v142
	v_and_b32_e32 v213, 0xffff0000, v142
	v_lshlrev_b32_e32 v214, 16, v143
	v_and_b32_e32 v215, 0xffff0000, v143
	s_waitcnt vmcnt(54)
	v_pk_fma_f32 v[208:209], v[208:209], v[40:41], v[212:213]
	v_pk_fma_f32 v[210:211], v[210:211], v[42:43], v[214:215]
	global_load_dwordx2 v[142:143], v220, s[10:11]
	s_add_u32 s10, s10, 0x8000
	s_addc_u32 s11, s11, 0
	global_load_dwordx4 v[40:43], v221, s[8:9] offset:3584
	s_add_u32 s8, s8, 0x1000
	s_addc_u32 s9, s9, 0
	v_cvt_pk_bf16_f32 v216, v208, v209
	v_cvt_pk_bf16_f32 v217, v210, v211
	global_store_dwordx2 v220, v[216:217], s[14:15]
	s_add_u32 s14, s14, 0x8000
	s_addc_u32 s15, s15, 0
	s_waitcnt vmcnt(56)
	v_lshlrev_b32_e32 v212, 16, v156
	v_and_b32_e32 v213, 0xffff0000, v156
	v_lshlrev_b32_e32 v214, 16, v157
	v_and_b32_e32 v215, 0xffff0000, v157
	s_waitcnt vmcnt(55)
	v_pk_fma_f32 v[208:209], v[208:209], v[44:45], v[212:213]
	v_pk_fma_f32 v[210:211], v[210:211], v[46:47], v[214:215]
	v_cvt_pk_bf16_f32 v218, v208, v209
	v_cvt_pk_bf16_f32 v219, v210, v211
	global_store_dwordx2 v220, v[218:219], s[14:15]
	s_add_u32 s14, s14, 0x8000
	s_addc_u32 s15, s15, 0
	s_waitcnt vmcnt(55)
	v_lshlrev_b32_e32 v212, 16, v158
	v_and_b32_e32 v213, 0xffff0000, v158
	v_lshlrev_b32_e32 v214, 16, v159
	v_and_b32_e32 v215, 0xffff0000, v159
	s_waitcnt vmcnt(54)
	v_pk_fma_f32 v[208:209], v[208:209], v[48:49], v[212:213]
	v_pk_fma_f32 v[210:211], v[210:211], v[50:51], v[214:215]
	v_cvt_pk_bf16_f32 v216, v208, v209
	v_cvt_pk_bf16_f32 v217, v210, v211
	global_store_dwordx2 v220, v[216:217], s[14:15]
	s_add_u32 s14, s14, 0x8000
	s_addc_u32 s15, s15, 0
	s_waitcnt vmcnt(54)
	v_lshlrev_b32_e32 v212, 16, v160
	v_and_b32_e32 v213, 0xffff0000, v160
	v_lshlrev_b32_e32 v214, 16, v161
	v_and_b32_e32 v215, 0xffff0000, v161
	s_waitcnt vmcnt(53)
	v_pk_fma_f32 v[208:209], v[208:209], v[52:53], v[212:213]
	v_pk_fma_f32 v[210:211], v[210:211], v[54:55], v[214:215]
	v_cvt_pk_bf16_f32 v218, v208, v209
	v_cvt_pk_bf16_f32 v219, v210, v211
	global_store_dwordx2 v220, v[218:219], s[14:15]
	s_add_u32 s14, s14, 0x8000
	s_addc_u32 s15, s15, 0
	s_waitcnt vmcnt(53)
; __device__ __forceinline__ unsigned pk2(float lo, float hi) { f32x2_t v = {lo, hi}; bf16x2_t b = __builtin_convertvector(v, bf16x2_t); return __builtin_bit_cast(unsigned, b); }
; __device__ __forceinline__ float bflo(unsigned u) { return __uint_as_float(u << 16); }
; __device__ __forceinline__ float bfhi(unsigned u) { return __uint_as_float(u & 0xffff0000u); }
; __device__ __forceinline__ void hgrn_scan_phase(const Args& a) {
;     ...
;         for (int c = 0; c < 32; ++c) {
;             const u32x2 u = st[(size_t)c * 4096]; const f32x4 dd = dc[c * 32];
;             u32x2 o; o.x = pk2(r0, r1); o.y = pk2(r2, r3); st[(size_t)c * 4096] = o;
;             r0 = dd.x * r0 + bflo(u.x); r1 = dd.y * r1 + bfhi(u.x); r2 = dd.z * r2 + bflo(u.y); r3 = dd.w * r3 + bfhi(u.y);
;         }
	v_lshlrev_b32_e32 v212, 16, v162
	v_and_b32_e32 v213, 0xffff0000, v162
	v_lshlrev_b32_e32 v214, 16, v163
	v_and_b32_e32 v215, 0xffff0000, v163
	s_waitcnt vmcnt(52)
	v_pk_fma_f32 v[208:209], v[208:209], v[56:57], v[212:213]
	v_pk_fma_f32 v[210:211], v[210:211], v[58:59], v[214:215]
	v_cvt_pk_bf16_f32 v216, v208, v209
	v_cvt_pk_bf16_f32 v217, v210, v211
	global_store_dwordx2 v220, v[216:217], s[14:15]
	s_add_u32 s14, s14, 0x8000
	s_addc_u32 s15, s15, 0
	s_waitcnt vmcnt(52)
	v_lshlrev_b32_e32 v212, 16, v164
	v_and_b32_e32 v213, 0xffff0000, v164
	v_lshlrev_b32_e32 v214, 16, v165
	v_and_b32_e32 v215, 0xffff0000, v165
	s_waitcnt vmcnt(51)
	v_pk_fma_f32 v[208:209], v[208:209], v[60:61], v[212:213]
	v_pk_fma_f32 v[210:211], v[210:211], v[62:63], v[214:215]
	v_cvt_pk_bf16_f32 v218, v208, v209
	v_cvt_pk_bf16_f32 v219, v210, v211
	global_store_dwordx2 v220, v[218:219], s[14:15]
	s_add_u32 s14, s14, 0x8000
	s_addc_u32 s15, s15, 0
	s_waitcnt vmcnt(51)
	v_lshlrev_b32_e32 v212, 16, v166
	v_and_b32_e32 v213, 0xffff0000, v166
	v_lshlrev_b32_e32 v214, 16, v167
	v_and_b32_e32 v215, 0xffff0000, v167
	s_waitcnt vmcnt(50)
	v_pk_fma_f32 v[208:209], v[208:209], v[64:65], v[212:213]
	v_pk_fma_f32 v[210:211], v[210:211], v[66:67], v[214:215]
	v_cvt_pk_bf16_f32 v216, v208, v209
	v_cvt_pk_bf16_f32 v217, v210, v211
	global_store_dwordx2 v220, v[216:217], s[14:15]
	s_add_u32 s14, s14, 0x8000
	s_addc_u32 s15, s15, 0
	s_waitcnt vmcnt(50)
	v_lshlrev_b32_e32 v212, 16, v168
	v_and_b32_e32 v213, 0xffff0000, v168
	v_lshlrev_b32_e32 v214, 16, v169
	v_and_b32_e32 v215, 0xffff0000, v169
	s_waitcnt vmcnt(49)
	v_pk_fma_f32 v[208:209], v[208:209], v[68:69], v[212:213]
	v_pk_fma_f32 v[210:211], v[210:211], v[70:71], v[214:215]
	v_cvt_pk_bf16_f32 v218, v208, v209
	v_cvt_pk_bf16_f32 v219, v210, v211
	global_store_dwordx2 v220, v[218:219], s[14:15]
	s_add_u32 s14, s14, 0x8000
	s_addc_u32 s15, s15, 0
	s_waitcnt vmcnt(49)
	v_lshlrev_b32_e32 v212, 16, v172
	v_and_b32_e32 v213, 0xffff0000, v172
	v_lshlrev_b32_e32 v214, 16, v173
	v_and_b32_e32 v215, 0xffff0000, v173
	s_waitcnt vmcnt(48)
	v_pk_fma_f32 v[208:209], v[208:209], v[72:73], v[212:213]
	v_pk_fma_f32 v[210:211], v[210:211], v[74:75], v[214:215]
	v_cvt_pk_bf16_f32 v216, v208, v209
	v_cvt_pk_bf16_f32 v217, v210, v211
	global_store_dwordx2 v220, v[216:217], s[14:15]
	s_add_u32 s14, s14, 0x8000
	s_addc_u32 s15, s15, 0
	s_waitcnt vmcnt(48)
	v_lshlrev_b32_e32 v212, 16, v174
	v_and_b32_e32 v213, 0xffff0000, v174
	v_lshlrev_b32_e32 v214, 16, v175
	v_and_b32_e32 v215, 0xffff0000, v175
	s_waitcnt vmcnt(47)
	v_pk_fma_f32 v[208:209], v[208:209], v[76:77], v[212:213]
	v_pk_fma_f32 v[210:211], v[210:211], v[78:79], v[214:215]
	v_cvt_pk_bf16_f32 v218, v208, v209
	v_cvt_pk_bf16_f32 v219, v210, v211
	global_store_dwordx2 v220, v[218:219], s[14:15]
	s_add_u32 s14, s14, 0x8000
	s_addc_u32 s15, s15, 0
	s_waitcnt vmcnt(47)
	v_lshlrev_b32_e32 v212, 16, v224
	v_and_b32_e32 v213, 0xffff0000, v224
	v_lshlrev_b32_e32 v214, 16, v225
	v_and_b32_e32 v215, 0xffff0000, v225
	s_waitcnt vmcnt(46)
	v_pk_fma_f32 v[208:209], v[208:209], v[84:85], v[212:213]
	v_pk_fma_f32 v[210:211], v[210:211], v[86:87], v[214:215]
	v_cvt_pk_bf16_f32 v216, v208, v209
	v_cvt_pk_bf16_f32 v217, v210, v211
	global_store_dwordx2 v220, v[216:217], s[14:15]
	s_add_u32 s14, s14, 0x8000
	s_addc_u32 s15, s15, 0
	s_waitcnt vmcnt(46)
	v_lshlrev_b32_e32 v212, 16, v200
	v_and_b32_e32 v213, 0xffff0000, v200
	v_lshlrev_b32_e32 v214, 16, v201
	v_and_b32_e32 v215, 0xffff0000, v201
	s_waitcnt vmcnt(45)
	v_pk_fma_f32 v[208:209], v[208:209], v[88:89], v[212:213]
	v_pk_fma_f32 v[210:211], v[210:211], v[90:91], v[214:215]
	v_cvt_pk_bf16_f32 v218, v208, v209
	v_cvt_pk_bf16_f32 v219, v210, v211
	global_store_dwordx2 v220, v[218:219], s[14:15]
	s_add_u32 s14, s14, 0x8000
	s_addc_u32 s15, s15, 0
	s_waitcnt vmcnt(45)
	v_lshlrev_b32_e32 v212, 16, v202
	v_and_b32_e32 v213, 0xffff0000, v202
	v_lshlrev_b32_e32 v214, 16, v203
	v_and_b32_e32 v215, 0xffff0000, v203
	s_waitcnt vmcnt(44)
	v_pk_fma_f32 v[208:209], v[208:209], v[92:93], v[212:213]
	v_pk_fma_f32 v[210:211], v[210:211], v[94:95], v[214:215]
	v_cvt_pk_bf16_f32 v216, v208, v209
	v_cvt_pk_bf16_f32 v217, v210, v211
	global_store_dwordx2 v220, v[216:217], s[14:15]
	s_add_u32 s14, s14, 0x8000
	s_addc_u32 s15, s15, 0
	s_waitcnt vmcnt(44)
	v_lshlrev_b32_e32 v212, 16, v204
	v_and_b32_e32 v213, 0xffff0000, v204
	v_lshlrev_b32_e32 v214, 16, v205
	v_and_b32_e32 v215, 0xffff0000, v205
	s_waitcnt vmcnt(43)
	v_pk_fma_f32 v[208:209], v[208:209], v[100:101], v[212:213]
	v_pk_fma_f32 v[210:211], v[210:211], v[102:103], v[214:215]
	v_cvt_pk_bf16_f32 v218, v208, v209
	v_cvt_pk_bf16_f32 v219, v210, v211
	global_store_dwordx2 v220, v[218:219], s[14:15]
	s_add_u32 s14, s14, 0x8000
	s_addc_u32 s15, s15, 0
	s_waitcnt vmcnt(43)
	v_lshlrev_b32_e32 v212, 16, v206
	v_and_b32_e32 v213, 0xffff0000, v206
	v_lshlrev_b32_e32 v214, 16, v207
	v_and_b32_e32 v215, 0xffff0000, v207
	s_waitcnt vmcnt(42)
; __device__ __forceinline__ unsigned pk2(float lo, float hi) { f32x2_t v = {lo, hi}; bf16x2_t b = __builtin_convertvector(v, bf16x2_t); return __builtin_bit_cast(unsigned, b); }
; __device__ __forceinline__ float bflo(unsigned u) { return __uint_as_float(u << 16); }
; __device__ __forceinline__ float bfhi(unsigned u) { return __uint_as_float(u & 0xffff0000u); }
; __device__ __forceinline__ void hgrn_scan_phase(const Args& a) {
;     ...
;         for (int c = 0; c < 32; ++c) {
;             const u32x2 u = st[(size_t)c * 4096]; const f32x4 dd = dc[c * 32];
;             u32x2 o; o.x = pk2(r0, r1); o.y = pk2(r2, r3); st[(size_t)c * 4096] = o;
;             r0 = dd.x * r0 + bflo(u.x); r1 = dd.y * r1 + bfhi(u.x); r2 = dd.z * r2 + bflo(u.y); r3 = dd.w * r3 + bfhi(u.y);
;         }
	v_pk_fma_f32 v[208:209], v[208:209], v[104:105], v[212:213]
	v_pk_fma_f32 v[210:211], v[210:211], v[106:107], v[214:215]
	v_cvt_pk_bf16_f32 v216, v208, v209
	v_cvt_pk_bf16_f32 v217, v210, v211
	global_store_dwordx2 v220, v[216:217], s[14:15]
	s_add_u32 s14, s14, 0x8000
	s_addc_u32 s15, s15, 0
	s_waitcnt vmcnt(42)
	v_lshlrev_b32_e32 v212, 16, v226
	v_and_b32_e32 v213, 0xffff0000, v226
	v_lshlrev_b32_e32 v214, 16, v227
	v_and_b32_e32 v215, 0xffff0000, v227
	s_waitcnt vmcnt(41)
	v_pk_fma_f32 v[208:209], v[208:209], v[108:109], v[212:213]
	v_pk_fma_f32 v[210:211], v[210:211], v[110:111], v[214:215]
	v_cvt_pk_bf16_f32 v218, v208, v209
	v_cvt_pk_bf16_f32 v219, v210, v211
	global_store_dwordx2 v220, v[218:219], s[14:15]
	s_add_u32 s14, s14, 0x8000
	s_addc_u32 s15, s15, 0
	s_waitcnt vmcnt(41)
	v_lshlrev_b32_e32 v212, 16, v228
	v_and_b32_e32 v213, 0xffff0000, v228
	v_lshlrev_b32_e32 v214, 16, v229
	v_and_b32_e32 v215, 0xffff0000, v229
	s_waitcnt vmcnt(40)
	v_pk_fma_f32 v[208:209], v[208:209], v[112:113], v[212:213]
	v_pk_fma_f32 v[210:211], v[210:211], v[114:115], v[214:215]
	v_cvt_pk_bf16_f32 v216, v208, v209
	v_cvt_pk_bf16_f32 v217, v210, v211
	global_store_dwordx2 v220, v[216:217], s[14:15]
	s_add_u32 s14, s14, 0x8000
	s_addc_u32 s15, s15, 0
	s_waitcnt vmcnt(39)
	v_lshlrev_b32_e32 v212, 16, v128
	v_and_b32_e32 v213, 0xffff0000, v128
	v_lshlrev_b32_e32 v214, 16, v129
	v_and_b32_e32 v215, 0xffff0000, v129
	s_waitcnt vmcnt(38)
	v_pk_fma_f32 v[208:209], v[208:209], v[12:13], v[212:213]
	v_pk_fma_f32 v[210:211], v[210:211], v[14:15], v[214:215]
	v_cvt_pk_bf16_f32 v218, v208, v209
	v_cvt_pk_bf16_f32 v219, v210, v211
	global_store_dwordx2 v220, v[218:219], s[14:15]
	s_add_u32 s14, s14, 0x8000
	s_addc_u32 s15, s15, 0
	s_waitcnt vmcnt(37)
	v_lshlrev_b32_e32 v212, 16, v130
	v_and_b32_e32 v213, 0xffff0000, v130
	v_lshlrev_b32_e32 v214, 16, v131
	v_and_b32_e32 v215, 0xffff0000, v131
	s_waitcnt vmcnt(36)
	v_pk_fma_f32 v[208:209], v[208:209], v[16:17], v[212:213]
	v_pk_fma_f32 v[210:211], v[210:211], v[18:19], v[214:215]
	v_cvt_pk_bf16_f32 v216, v208, v209
	v_cvt_pk_bf16_f32 v217, v210, v211
	global_store_dwordx2 v220, v[216:217], s[14:15]
	s_add_u32 s14, s14, 0x8000
	s_addc_u32 s15, s15, 0
	s_waitcnt vmcnt(35)
	v_lshlrev_b32_e32 v212, 16, v132
	v_and_b32_e32 v213, 0xffff0000, v132
	v_lshlrev_b32_e32 v214, 16, v133
	v_and_b32_e32 v215, 0xffff0000, v133
	s_waitcnt vmcnt(34)
	v_pk_fma_f32 v[208:209], v[208:209], v[20:21], v[212:213]
	v_pk_fma_f32 v[210:211], v[210:211], v[22:23], v[214:215]
	v_cvt_pk_bf16_f32 v218, v208, v209
	v_cvt_pk_bf16_f32 v219, v210, v211
	global_store_dwordx2 v220, v[218:219], s[14:15]
	s_add_u32 s14, s14, 0x8000
	s_addc_u32 s15, s15, 0
	s_waitcnt vmcnt(33)
	v_lshlrev_b32_e32 v212, 16, v134
	v_and_b32_e32 v213, 0xffff0000, v134
	v_lshlrev_b32_e32 v214, 16, v135
	v_and_b32_e32 v215, 0xffff0000, v135
	s_waitcnt vmcnt(32)
	v_pk_fma_f32 v[208:209], v[208:209], v[24:25], v[212:213]
	v_pk_fma_f32 v[210:211], v[210:211], v[26:27], v[214:215]
	v_cvt_pk_bf16_f32 v216, v208, v209
	v_cvt_pk_bf16_f32 v217, v210, v211
	global_store_dwordx2 v220, v[216:217], s[14:15]
	s_add_u32 s14, s14, 0x8000
	s_addc_u32 s15, s15, 0
	s_waitcnt vmcnt(31)
	v_lshlrev_b32_e32 v212, 16, v136
	v_and_b32_e32 v213, 0xffff0000, v136
	v_lshlrev_b32_e32 v214, 16, v137
	v_and_b32_e32 v215, 0xffff0000, v137
	s_waitcnt vmcnt(30)
	v_pk_fma_f32 v[208:209], v[208:209], v[28:29], v[212:213]
	v_pk_fma_f32 v[210:211], v[210:211], v[30:31], v[214:215]
	v_cvt_pk_bf16_f32 v218, v208, v209
	v_cvt_pk_bf16_f32 v219, v210, v211
	global_store_dwordx2 v220, v[218:219], s[14:15]
	s_add_u32 s14, s14, 0x8000
	s_addc_u32 s15, s15, 0
	s_waitcnt vmcnt(29)
	v_lshlrev_b32_e32 v212, 16, v138
	v_and_b32_e32 v213, 0xffff0000, v138
	v_lshlrev_b32_e32 v214, 16, v139
	v_and_b32_e32 v215, 0xffff0000, v139
	s_waitcnt vmcnt(28)
	v_pk_fma_f32 v[208:209], v[208:209], v[32:33], v[212:213]
	v_pk_fma_f32 v[210:211], v[210:211], v[34:35], v[214:215]
	v_cvt_pk_bf16_f32 v216, v208, v209
	v_cvt_pk_bf16_f32 v217, v210, v211
	global_store_dwordx2 v220, v[216:217], s[14:15]
	s_add_u32 s14, s14, 0x8000
	s_addc_u32 s15, s15, 0
	s_waitcnt vmcnt(27)
	v_lshlrev_b32_e32 v212, 16, v140
	v_and_b32_e32 v213, 0xffff0000, v140
	v_lshlrev_b32_e32 v214, 16, v141
	v_and_b32_e32 v215, 0xffff0000, v141
	s_waitcnt vmcnt(26)
	v_pk_fma_f32 v[208:209], v[208:209], v[36:37], v[212:213]
	v_pk_fma_f32 v[210:211], v[210:211], v[38:39], v[214:215]
	v_cvt_pk_bf16_f32 v218, v208, v209
	v_cvt_pk_bf16_f32 v219, v210, v211
	global_store_dwordx2 v220, v[218:219], s[14:15]
	s_add_u32 s14, s14, 0x8000
	s_addc_u32 s15, s15, 0
	s_waitcnt vmcnt(25)
	v_lshlrev_b32_e32 v212, 16, v142
	v_and_b32_e32 v213, 0xffff0000, v142
	v_lshlrev_b32_e32 v214, 16, v143
	v_and_b32_e32 v215, 0xffff0000, v143
	s_waitcnt vmcnt(24)
	v_pk_fma_f32 v[208:209], v[208:209], v[40:41], v[212:213]
	v_pk_fma_f32 v[210:211], v[210:211], v[42:43], v[214:215]
	s_branch .LBB0_527

; __device__ __forceinline__ unsigned xb_ld(unsigned* p)              { return __hip_atomic_load(p, __ATOMIC_RELAXED, __HIP_MEMORY_SCOPE_AGENT); }
; __device__ __forceinline__ unsigned xb_add(unsigned* p, unsigned v) { return __hip_atomic_fetch_add(p, v, __ATOMIC_RELAXED, __HIP_MEMORY_SCOPE_AGENT); }
; #define XB_SPIN(cond, bar) do { unsigned _sp = 0; while (cond) { __builtin_amdgcn_s_sleep(1); \
;     if ((++_sp & 255u) == 0u) { if (xb_ld(&(bar)[XB_TMO])) break; if (_sp > XB_SPIN_CAP) { atomicAdd(&(bar)[XB_TMO], 1u); break; } } } } while (0)
; __device__ __forceinline__ void xcd_barrier(const XcdBarrier& b) {
;     asm volatile("s_waitcnt vmcnt(0)" ::: "memory");
;     __syncthreads();
;     if (threadIdx.x == 0) {
;         unsigned* bar = b.bar;
;         __builtin_amdgcn_s_waitcnt(0);
;         unsigned nloc = b.st[0], nx = b.st[1];
;         if (nloc == 0u) { xcd_barrier_complete(bar, b.x, nloc, nx); b.st[0] = nloc; b.st[1] = nx; }
;         const unsigned old = xb_add(&bar[XB_XSUB(b.x)], 1u);
;         const unsigned gen = old / nloc;
;         if (old + 1u == (gen + 1u) * nloc) {
;             __builtin_amdgcn_fence(__ATOMIC_RELEASE, "agent");
;             asm volatile("s_waitcnt vmcnt(0)" ::: "memory");
;             const unsigned og = xb_add(&bar[XB_TOP], 1u);
;             const unsigned tg = og / nx;
;             if (og + 1u == (tg + 1u) * nx) xb_add(&bar[XB_TOPGEN], 1u);
;             else XB_SPIN(xb_ld(&bar[XB_TOPGEN]) == tg, bar);
;             __builtin_amdgcn_fence(__ATOMIC_ACQUIRE, "agent");
;             xb_add(&bar[XB_XGEN(b.x)], 1u);
;             asm volatile("s_waitcnt vmcnt(0)" ::: "memory");
;         } else {
;             XB_SPIN(xb_ld(&bar[XB_XGEN(b.x)]) == gen, bar);
;             __builtin_amdgcn_fence(__ATOMIC_ACQUIRE, "agent");
;             asm volatile("s_waitcnt vmcnt(0)" ::: "memory");
;         }
;     }
;     __syncthreads();
; }
.Lbbsb:
	s_waitcnt vmcnt(0) lgkmcnt(0)
	s_barrier
	s_add_u32 s8, s78, 0xfc00000
	s_addc_u32 s9, s79, 0
	s_and_b32 s5, s2, 7
	s_lshl_b32 s5, s5, 6
	s_add_i32 s101, s101, 1
	s_lshl_b32 s6, s101, 5
	v_cmp_eq_u32_e32 vcc, 0, v178
	s_and_saveexec_b64 s[14:15], vcc
	s_cbranch_execz .Lbbsb_join
	v_mov_b32_e32 v0, s5
	v_mov_b32_e32 v2, 1
	s_cmp_lg_u32 s100, 0
	s_cbranch_scc1 .Lbbsb_known
	global_load_dword v1, v0, s[8:9] offset:32 sc1
	s_waitcnt vmcnt(0)
	v_readfirstlane_b32 s16, v1
	s_bcnt1_i32_b32 s16, s16
	s_cmp_eq_u32 s16, 1
	s_cselect_b32 s100, 1, 2
.Lbbsb_known:
	s_cmp_eq_u32 s100, 1
	s_cbranch_scc1 .Lbbsb_fast
	buffer_wbl2 sc1
	s_waitcnt vmcnt(0)
.Lbbsb_fast:
	global_atomic_add v0, v2, s[8:9]
	s_mov_b32 s10, 0
.Lbbsb_spin:
	global_load_dword v1, v0, s[8:9] sc1
	s_waitcnt vmcnt(0)
	v_readfirstlane_b32 s11, v1
	s_cmp_ge_u32 s11, s6
	s_cbranch_scc1 .Lbbsb_done
	s_sleep 1
	s_add_i32 s10, s10, 1
	s_cmp_lt_u32 s10, 0x2000
	s_cbranch_scc1 .Lbbsb_spin
